# whole-cache-line LDS-DMA piece layout (8 rows x 128B per 1KB piece, XOR chunk swizzle) extended from FFN-up GEMM to in-proj, out-proj and FFN-down GEMMs
# speedup vs baseline: 1.0048x; 1.0001x over previous
.LBB0_137:
	v_lshrrev_b32_e32 v1, 3, v237
	s_andn2_b64 vcc, exec, s[2:3]
	v_lshlrev_b32_e32 v216, 2, v0
	s_cbranch_vccnz .LBB0_513
	v_lshrrev_b32_e32 v4, 1, v0
	v_and_b32_e32 v13, 24, v4
	v_lshrrev_b32_e32 v4, 5, v0
	v_lshlrev_b32_e32 v2, 4, v0
	v_and_b32_e32 v3, 32, v0
	v_and_b32_e32 v4, 4, v4
	v_bfe_u32 v5, v0, 2, 2
	s_add_u32 s19, s68, 0x8c00000
	v_bfe_u32 v12, v0, 2, 4
	v_bitop3_b32 v10, v2, v3, 48 bitop3:0x6c
	v_and_b32_e32 v11, 64, v0
	v_or3_b32 v4, v4, v5, v13
	v_lshrrev_b32_e32 v5, 3, v0
	v_or_b32_e32 v14, 0x2000, v2
	s_addc_u32 s36, s69, 0
	v_or_b32_e32 v3, v10, v11
	v_and_or_b32 v6, v5, 48, v12
	v_and_or_b32 v5, v5, 32, v4
	v_lshrrev_b32_e32 v2, 7, v14
	s_movk_i32 s1, 0x70
	s_add_u32 s37, s68, 0x200000
	v_lshl_or_b32 v148, v5, 12, v3
	v_and_or_b32 v5, v2, s1, v12
	s_movk_i32 s1, 0x60
	s_addc_u32 s38, s69, 0
	v_and_or_b32 v2, v2, s1, v4
	s_lshr_b32 s3, s8, 6
	s_ashr_i32 s5, s4, 31
	s_ashr_i32 s1, s0, 31
	s_lshr_b32 s2, s8, 8
	s_lshl_b32 s39, s3, 10
	s_lshl_b64 s[6:7], s[4:5], 20
	s_lshl_b64 s[10:11], s[0:1], 20
	s_add_u32 s28, s37, s10
	s_addc_u32 s29, s38, s11
	s_add_i32 s40, s39, 0
	s_add_i32 m0, s40, 0x10000
	v_lshl_or_b32 v152, v2, 12, v3
	v_lshrrev_b32_e32 v240, 6, v0
	v_bfe_u32 v241, v0, 3, 3
	v_and_b32_e32 v242, 7, v0
	v_lshrrev_b32_e32 v243, 1, v241
	v_and_b32_e32 v244, 1, v240
	v_lshl_or_b32 v243, v244, 2, v243
	v_xor_b32_e32 v242, v242, v243
	v_lshlrev_b32_e32 v242, 4, v242
	v_lshl_add_u32 v245, v240, 3, v241
	v_lshrrev_b32_e32 v246, 2, v240
	v_lshlrev_b32_e32 v246, 5, v246
	v_lshl_add_u32 v246, v244, 4, v246
	v_lshrrev_b32_e32 v247, 2, v241
	v_lshl_add_u32 v246, v247, 3, v246
	v_bfe_u32 v247, v240, 1, 1
	v_lshl_add_u32 v246, v247, 2, v246
	v_and_b32_e32 v247, 3, v241
	v_add_u32_e32 v246, v246, v247
	v_lshl_add_u32 v146, v245, 12, v242
	v_lshl_add_u32 v148, v246, 12, v242
	v_add_u32_e32 v150, 0x40000, v146
	v_add_u32_e32 v152, 0x40000, v148
	global_load_lds_dwordx4 v148, s[28:29]
	s_add_i32 m0, s40, 0x12000
	s_add_u32 s10, s28, 0x80000
	global_load_lds_dwordx4 v152, s[28:29]
	s_addc_u32 s11, s29, 0
	s_add_i32 m0, s40, 0x14000
	s_nop 0
	global_load_lds_dwordx4 v148, s[10:11]
	s_add_i32 m0, s40, 0x16000
	s_add_u32 s6, s19, s6
	s_addc_u32 s7, s36, s7
	s_add_i32 s41, s40, 0x2000
	global_load_lds_dwordx4 v152, s[10:11]
	s_mov_b32 m0, s40
	s_add_u32 s10, s6, 0x80000
	s_nop 0
	global_load_lds_dwordx4 v146, s[6:7]
	s_mov_b32 m0, s41
	s_addc_u32 s11, s7, 0
	s_add_i32 s42, s40, 0x4000
	global_load_lds_dwordx4 v150, s[6:7]
	s_mov_b32 m0, s42
	s_add_i32 s43, s40, 0x6000
	global_load_lds_dwordx4 v146, s[10:11]
	s_mov_b32 m0, s43
	v_mov_b32_e32 v155, 0
	global_load_lds_dwordx4 v150, s[10:11]
	v_mov_b32_e32 v149, v155
	v_mov_b32_e32 v153, v155
	v_mov_b32_e32 v147, v155
	v_mov_b32_e32 v151, v155
	s_cmp_eq_u32 s2, 1
	s_mov_b32 s44, 0
	v_lshl_add_u64 v[8:9], s[28:29], 0, v[148:149]
	v_lshl_add_u64 v[6:7], s[28:29], 0, v[152:153]
	v_lshl_add_u64 v[2:3], s[6:7], 0, v[146:147]
	s_cselect_b64 s[24:25], -1, 0
	s_cmp_lg_u32 s2, 1
	v_lshl_add_u64 v[4:5], s[6:7], 0, v[150:151]
	s_cbranch_scc1 .LBB0_140
	s_barrier
.LBB0_140:
	s_add_u32 s10, s68, 0xb000000
	s_addc_u32 s11, s69, 0
	s_add_u32 s12, s68, 0x16800000
	v_writelane_b32 v254, s68, 57
	s_addc_u32 s13, s69, 0
	s_add_u32 s45, s90, 0x4080000
	s_addc_u32 s46, s91, 0
	s_add_u32 s47, s90, 0x6080000
	s_addc_u32 s48, s91, 0
	s_add_u32 s49, s90, 0x8280000
	s_addc_u32 s50, s91, 0
	v_writelane_b32 v254, s69, 58
	s_add_u32 s51, s90, 0x82c0000
	s_addc_u32 s84, s91, 0
	v_readlane_b32 s1, v254, 2
	s_lshl_b32 s3, s3, 5
	s_mov_b64 s[14:15], 0x80
	s_ashr_i32 s71, s1, 31
	v_readlane_b32 s1, v254, 56
	s_and_b32 s3, s3, 0x60
	s_add_i32 m0, s40, 0x18000
	v_lshl_add_u64 v[8:9], v[8:9], 0, s[14:15]
	s_ashr_i32 s74, s1, 31
	s_lshl_b32 s1, s2, 13
	s_lshl_b32 s5, s3, 7
	s_waitcnt vmcnt(2)
	s_barrier
	global_load_lds_dwordx4 v[8:9], off
	v_lshl_add_u64 v[6:7], v[6:7], 0, s[14:15]
	s_add_i32 m0, s40, 0x1a000
	s_add_i32 s87, s40, 0x8000
	s_add_i32 s92, s40, 0xa000
	global_load_lds_dwordx4 v[6:7], off
	v_lshl_add_u64 v[2:3], v[2:3], 0, s[14:15]
	s_mov_b32 m0, s87
	s_add_u32 s16, s28, 0x80080
	global_load_lds_dwordx4 v[2:3], off
	v_lshl_add_u64 v[2:3], v[4:5], 0, s[14:15]
	s_mov_b32 m0, s92
	s_addc_u32 s17, s29, 0
	global_load_lds_dwordx4 v[2:3], off
	s_add_i32 m0, s40, 0x1c000
	v_lshl_add_u64 v[2:3], s[16:17], 0, v[148:149]
	global_load_lds_dwordx4 v[2:3], off
	v_lshl_add_u64 v[2:3], s[16:17], 0, v[152:153]
	s_add_i32 m0, s40, 0x1e000
	v_lshlrev_b32_e32 v4, 6, v0
	global_load_lds_dwordx4 v[2:3], off
	v_and_b32_e32 v2, 15, v0
	v_lshlrev_b32_e32 v3, 1, v13
	s_movk_i32 s9, 0x3c0
	v_and_or_b32 v4, v4, s9, v3
	v_and_b32_e32 v5, 32, v216
	v_lshl_or_b32 v217, s2, 6, v2
	v_lshl_or_b32 v2, v2, 6, v3
	v_lshlrev_b32_e32 v3, 9, v0
	v_bitop3_b32 v218, s5, v4, v5 bitop3:0xf6
	v_and_b32_e32 v3, 0x30000, v3
	v_lshlrev_b32_e32 v4, 12, v12
	v_or3_b32 v3, v10, v3, v4
	v_add_u32_e32 v156, v3, v11
	v_lshlrev_b32_e32 v3, 5, v14
	s_waitcnt vmcnt(6)
	s_cmpk_lt_u32 s8, 0x100
	v_and_b32_e32 v3, 0x70000, v3
	v_bitop3_b32 v2, v2, s1, v5 bitop3:0xde
	s_cselect_b64 s[88:89], -1, 0
	v_or3_b32 v3, v10, v3, v4
	s_add_i32 s94, 0, 0x10000
	s_add_i32 s96, 0, 0x14000
	v_or_b32_e32 v219, s3, v13
	v_mov_b32_e32 v157, v155
	v_add_u32_e32 v158, v3, v11
	v_mov_b32_e32 v159, v155
	v_mov_b64_e32 v[160:161], 0x5ac
	v_mov_b64_e32 v[162:163], 0x5ab
	v_add_u32_e32 v220, s94, v218
	v_add_u32_e32 v221, s96, v218
	v_add_u32_e32 v222, 0, v2
	s_mov_b32 s18, 0x3e38aa3b
	s_movk_i32 s97, 0x1fff
	s_movk_i32 s75, 0x2040
	s_movk_i32 s8, 0x5800
	s_movk_i32 s90, 0x1f7f
	s_movk_i32 s91, 0x1f6f
	s_movk_i32 s93, 0x1f5f
	s_mov_b32 s9, 0x3fb8aa3b
	s_mov_b32 s95, 0xc2ce8ed0
	s_mov_b32 s85, 0x42b17218
	s_mov_b32 s86, 0x7f800000
	s_mov_b32 s16, 0x800000
	s_mov_b32 s17, 0x3f317217
	v_mov_b32_e32 v223, 0x7f800000
	v_mov_b32_e32 v224, 0x41b17218
	s_mov_b64 s[72:73], s[24:25]
	s_barrier
	v_mov_b32_e32 v156, v146
	v_mov_b32_e32 v158, v150
	v_and_b32_e32 v240, 63, v0
	v_and_b32_e32 v241, 15, v240
	v_lshrrev_b32_e32 v242, 4, v240
	v_lshrrev_b32_e32 v243, 3, v241
	v_lshlrev_b32_e32 v243, 10, v243
	v_and_b32_e32 v244, 7, v241
	v_lshl_add_u32 v243, v244, 7, v243
	v_lshrrev_b32_e32 v244, 1, v241
	v_xor_b32_e32 v245, v242, v244
	v_lshl_add_u32 v245, v245, 4, v243
	v_xor_b32_e32 v246, 64, v245
	v_lshrrev_b32_e32 v247, 6, v0
	v_lshrrev_b32_e32 v244, 2, v247
	v_lshl_add_u32 v222, v244, 13, v245
	v_lshl_add_u32 v248, v244, 13, v246
	v_and_b32_e32 v244, 3, v247
	v_lshl_add_u32 v218, v244, 12, v245
	v_lshl_add_u32 v249, v244, 12, v246
	v_add_u32_e32 v220, s94, v218
	v_add_u32_e32 v250, s94, v249
	v_add_u32_e32 v221, s96, v218
	v_add_u32_e32 v251, s96, v249
	s_branch .LBB0_143

.LBB0_150:
	ds_read_b128 v[130:133], v220
	ds_read_b128 v[134:137], v250
	ds_read_b128 v[138:141], v220 offset:2048
	ds_read_b128 v[142:145], v250 offset:2048
	ds_read_b128 v[164:167], v221
	ds_read_b128 v[168:171], v251
	ds_read_b128 v[172:175], v221 offset:2048
	ds_read_b128 v[176:179], v251 offset:2048
	s_add_u32 s28, s6, 0xfff80080
	s_addc_u32 s29, s7, -1
	s_cmp_eq_u32 s35, 28
	s_cselect_b32 s31, s1, s29
	s_cselect_b32 s30, s5, s28
	s_cselect_b32 s29, s21, s34
	s_cselect_b32 s28, s23, s33
	s_add_i32 m0, s40, 0xc000
	ds_read_b128 v[180:183], v222
	ds_read_b128 v[184:187], v248
	ds_read_b128 v[188:191], v222 offset:2048
	ds_read_b128 v[192:195], v248 offset:2048
	ds_read_b128 v[196:199], v222 offset:4096
	ds_read_b128 v[200:203], v248 offset:4096
	ds_read_b128 v[204:207], v222 offset:6144
	ds_read_b128 v[208:211], v248 offset:6144
	global_load_lds_dwordx4 v156, s[6:7]
	s_add_i32 m0, s40, 0xe000
	s_nop 0
	global_load_lds_dwordx4 v158, s[6:7]
	s_waitcnt vmcnt(8)
	s_waitcnt lgkmcnt(0)
	s_barrier
	s_setprio 1
	s_waitcnt lgkmcnt(0)
	v_mfma_f32_16x16x32_bf16 v[126:129], v[130:133], v[180:183], v[126:129]
	v_mfma_f32_16x16x32_bf16 v[122:125], v[138:141], v[180:183], v[122:125]
	v_mfma_f32_16x16x32_bf16 v[110:113], v[130:133], v[188:191], v[110:113]
	v_mfma_f32_16x16x32_bf16 v[106:109], v[138:141], v[188:191], v[106:109]
	v_mfma_f32_16x16x32_bf16 v[94:97], v[130:133], v[196:199], v[94:97]
	v_mfma_f32_16x16x32_bf16 v[90:93], v[138:141], v[196:199], v[90:93]
	v_mfma_f32_16x16x32_bf16 v[78:81], v[130:133], v[204:207], v[78:81]
	v_mfma_f32_16x16x32_bf16 v[74:77], v[138:141], v[204:207], v[74:77]
	v_mfma_f32_16x16x32_bf16 v[126:129], v[134:137], v[184:187], v[126:129]
	v_mfma_f32_16x16x32_bf16 v[122:125], v[142:145], v[184:187], v[122:125]
	v_mfma_f32_16x16x32_bf16 v[110:113], v[134:137], v[192:195], v[110:113]
	v_mfma_f32_16x16x32_bf16 v[106:109], v[142:145], v[192:195], v[106:109]
	v_mfma_f32_16x16x32_bf16 v[94:97], v[134:137], v[200:203], v[94:97]
	v_mfma_f32_16x16x32_bf16 v[90:93], v[142:145], v[200:203], v[90:93]
	v_mfma_f32_16x16x32_bf16 v[78:81], v[134:137], v[208:211], v[78:81]
	v_mfma_f32_16x16x32_bf16 v[74:77], v[142:145], v[208:211], v[74:77]
	s_setprio 0
	s_setprio 1
	v_mfma_f32_16x16x32_bf16 v[118:121], v[164:167], v[180:183], v[118:121]
	v_mfma_f32_16x16x32_bf16 v[114:117], v[172:175], v[180:183], v[114:117]
	v_mfma_f32_16x16x32_bf16 v[102:105], v[164:167], v[188:191], v[102:105]
	v_mfma_f32_16x16x32_bf16 v[98:101], v[172:175], v[188:191], v[98:101]
	v_mfma_f32_16x16x32_bf16 v[86:89], v[164:167], v[196:199], v[86:89]
	v_mfma_f32_16x16x32_bf16 v[82:85], v[172:175], v[196:199], v[82:85]
	v_mfma_f32_16x16x32_bf16 v[70:73], v[164:167], v[204:207], v[70:73]
	v_mfma_f32_16x16x32_bf16 v[66:69], v[172:175], v[204:207], v[66:69]
	v_mfma_f32_16x16x32_bf16 v[118:121], v[168:171], v[184:187], v[118:121]
	v_mfma_f32_16x16x32_bf16 v[114:117], v[176:179], v[184:187], v[114:117]
	v_mfma_f32_16x16x32_bf16 v[102:105], v[168:171], v[192:195], v[102:105]
	v_mfma_f32_16x16x32_bf16 v[98:101], v[176:179], v[192:195], v[98:101]
	v_mfma_f32_16x16x32_bf16 v[86:89], v[168:171], v[200:203], v[86:89]
	v_mfma_f32_16x16x32_bf16 v[82:85], v[176:179], v[200:203], v[82:85]
	v_mfma_f32_16x16x32_bf16 v[70:73], v[168:171], v[208:211], v[70:73]
	v_mfma_f32_16x16x32_bf16 v[66:69], v[176:179], v[208:211], v[66:69]
	s_setprio 0
	s_barrier
	s_add_i32 s68, s94, s39
	s_mov_b32 m0, s68
	ds_read_b128 v[180:183], v222 offset:16384
	ds_read_b128 v[184:187], v248 offset:16384
	ds_read_b128 v[188:191], v222 offset:18432
	ds_read_b128 v[192:195], v248 offset:18432
	ds_read_b128 v[196:199], v222 offset:20480
	ds_read_b128 v[200:203], v248 offset:20480
	ds_read_b128 v[204:207], v222 offset:22528
	ds_read_b128 v[208:211], v248 offset:22528
	global_load_lds_dwordx4 v148, s[28:29]
	s_add_i32 m0, s68, 0x2000
	s_add_u32 s68, s28, 0x80000
	s_addc_u32 s69, s29, 0
	s_add_i32 s70, s96, s39
	global_load_lds_dwordx4 v152, s[28:29]
	s_mov_b32 m0, s70
	s_nop 0
	global_load_lds_dwordx4 v148, s[68:69]
	s_add_i32 m0, s70, 0x2000
	s_nop 0
	global_load_lds_dwordx4 v152, s[68:69]
	s_mov_b32 m0, s40
	s_nop 0
	global_load_lds_dwordx4 v146, s[30:31]
	s_mov_b32 m0, s41
	s_nop 0
	global_load_lds_dwordx4 v150, s[30:31]
	s_waitcnt vmcnt(8)
	s_waitcnt lgkmcnt(0)
	s_barrier
	s_setprio 1
	s_waitcnt lgkmcnt(0)
	v_mfma_f32_16x16x32_bf16 v[62:65], v[130:133], v[180:183], v[62:65]
	v_mfma_f32_16x16x32_bf16 v[58:61], v[138:141], v[180:183], v[58:61]
	v_mfma_f32_16x16x32_bf16 v[46:49], v[130:133], v[188:191], v[46:49]
	v_mfma_f32_16x16x32_bf16 v[42:45], v[138:141], v[188:191], v[42:45]
	v_mfma_f32_16x16x32_bf16 v[30:33], v[130:133], v[196:199], v[30:33]
	v_mfma_f32_16x16x32_bf16 v[26:29], v[138:141], v[196:199], v[26:29]
	v_mfma_f32_16x16x32_bf16 v[14:17], v[130:133], v[204:207], v[14:17]
	v_mfma_f32_16x16x32_bf16 v[10:13], v[138:141], v[204:207], v[10:13]
	v_mfma_f32_16x16x32_bf16 v[62:65], v[134:137], v[184:187], v[62:65]
	v_mfma_f32_16x16x32_bf16 v[58:61], v[142:145], v[184:187], v[58:61]
	v_mfma_f32_16x16x32_bf16 v[46:49], v[134:137], v[192:195], v[46:49]
	v_mfma_f32_16x16x32_bf16 v[42:45], v[142:145], v[192:195], v[42:45]
	v_mfma_f32_16x16x32_bf16 v[30:33], v[134:137], v[200:203], v[30:33]
	v_mfma_f32_16x16x32_bf16 v[26:29], v[142:145], v[200:203], v[26:29]
	v_mfma_f32_16x16x32_bf16 v[14:17], v[134:137], v[208:211], v[14:17]
	v_mfma_f32_16x16x32_bf16 v[10:13], v[142:145], v[208:211], v[10:13]
	s_setprio 0
	s_setprio 1
	v_mfma_f32_16x16x32_bf16 v[54:57], v[164:167], v[180:183], v[54:57]
	v_mfma_f32_16x16x32_bf16 v[50:53], v[172:175], v[180:183], v[50:53]
	v_mfma_f32_16x16x32_bf16 v[38:41], v[164:167], v[188:191], v[38:41]
	v_mfma_f32_16x16x32_bf16 v[34:37], v[172:175], v[188:191], v[34:37]
	v_mfma_f32_16x16x32_bf16 v[22:25], v[164:167], v[196:199], v[22:25]
	v_mfma_f32_16x16x32_bf16 v[18:21], v[172:175], v[196:199], v[18:21]
	v_mfma_f32_16x16x32_bf16 v[6:9], v[164:167], v[204:207], v[6:9]
	v_mfma_f32_16x16x32_bf16 v[2:5], v[172:175], v[204:207], v[2:5]
	v_mfma_f32_16x16x32_bf16 v[54:57], v[168:171], v[184:187], v[54:57]
	v_mfma_f32_16x16x32_bf16 v[50:53], v[176:179], v[184:187], v[50:53]
	v_mfma_f32_16x16x32_bf16 v[38:41], v[168:171], v[192:195], v[38:41]
	v_mfma_f32_16x16x32_bf16 v[34:37], v[176:179], v[192:195], v[34:37]
	v_mfma_f32_16x16x32_bf16 v[22:25], v[168:171], v[200:203], v[22:25]
	v_mfma_f32_16x16x32_bf16 v[18:21], v[176:179], v[200:203], v[18:21]
	v_mfma_f32_16x16x32_bf16 v[6:9], v[168:171], v[208:211], v[6:9]
	v_mfma_f32_16x16x32_bf16 v[2:5], v[176:179], v[208:211], v[2:5]
	s_setprio 0
	s_barrier
	s_add_i32 s68, 0, 0x18000
	s_add_i32 s69, 0, 0x1c000
	v_add_u32_e32 v142, s68, v218
	v_add_u32_e32 v252, s68, v249
	v_add_u32_e32 v154, s69, v218
	v_add_u32_e32 v253, s69, v249
	ds_read_b128 v[130:133], v142
	ds_read_b128 v[134:137], v252
	ds_read_b128 v[138:141], v142 offset:2048
	ds_read_b128 v[142:145], v252 offset:2048
	ds_read_b128 v[164:167], v154
	ds_read_b128 v[168:171], v253
	ds_read_b128 v[172:175], v154 offset:2048
	ds_read_b128 v[176:179], v253 offset:2048
	s_add_u32 s30, s30, 0x80000
	s_addc_u32 s31, s31, 0
	s_add_u32 s100, s30, 0xfff80080
	s_addc_u32 s101, s31, -1
	s_mov_b32 m0, s42
	ds_read_b128 v[180:183], v222 offset:32768
	ds_read_b128 v[184:187], v248 offset:32768
	ds_read_b128 v[188:191], v222 offset:34816
	ds_read_b128 v[192:195], v248 offset:34816
	ds_read_b128 v[196:199], v222 offset:36864
	ds_read_b128 v[200:203], v248 offset:36864
	ds_read_b128 v[204:207], v222 offset:38912
	ds_read_b128 v[208:211], v248 offset:38912
	global_load_lds_dwordx4 v146, s[30:31]
	s_mov_b32 m0, s43
	s_nop 0
	global_load_lds_dwordx4 v150, s[30:31]
	s_waitcnt vmcnt(8)
	s_waitcnt lgkmcnt(0)
	s_barrier
	s_setprio 1
	s_waitcnt lgkmcnt(0)
	v_mfma_f32_16x16x32_bf16 v[126:129], v[130:133], v[180:183], v[126:129]
	v_mfma_f32_16x16x32_bf16 v[122:125], v[138:141], v[180:183], v[122:125]
	v_mfma_f32_16x16x32_bf16 v[110:113], v[130:133], v[188:191], v[110:113]
	v_mfma_f32_16x16x32_bf16 v[106:109], v[138:141], v[188:191], v[106:109]
	v_mfma_f32_16x16x32_bf16 v[94:97], v[130:133], v[196:199], v[94:97]
	v_mfma_f32_16x16x32_bf16 v[90:93], v[138:141], v[196:199], v[90:93]
	v_mfma_f32_16x16x32_bf16 v[78:81], v[130:133], v[204:207], v[78:81]
	v_mfma_f32_16x16x32_bf16 v[74:77], v[138:141], v[204:207], v[74:77]
	v_mfma_f32_16x16x32_bf16 v[126:129], v[134:137], v[184:187], v[126:129]
	v_mfma_f32_16x16x32_bf16 v[122:125], v[142:145], v[184:187], v[122:125]
	v_mfma_f32_16x16x32_bf16 v[110:113], v[134:137], v[192:195], v[110:113]
	v_mfma_f32_16x16x32_bf16 v[106:109], v[142:145], v[192:195], v[106:109]
	v_mfma_f32_16x16x32_bf16 v[94:97], v[134:137], v[200:203], v[94:97]
	v_mfma_f32_16x16x32_bf16 v[90:93], v[142:145], v[200:203], v[90:93]
	v_mfma_f32_16x16x32_bf16 v[78:81], v[134:137], v[208:211], v[78:81]
	v_mfma_f32_16x16x32_bf16 v[74:77], v[142:145], v[208:211], v[74:77]
	s_setprio 0
	s_setprio 1
	v_mfma_f32_16x16x32_bf16 v[118:121], v[164:167], v[180:183], v[118:121]
	v_mfma_f32_16x16x32_bf16 v[114:117], v[172:175], v[180:183], v[114:117]
	v_mfma_f32_16x16x32_bf16 v[102:105], v[164:167], v[188:191], v[102:105]
	v_mfma_f32_16x16x32_bf16 v[98:101], v[172:175], v[188:191], v[98:101]
	v_mfma_f32_16x16x32_bf16 v[86:89], v[164:167], v[196:199], v[86:89]
	v_mfma_f32_16x16x32_bf16 v[82:85], v[172:175], v[196:199], v[82:85]
	v_mfma_f32_16x16x32_bf16 v[70:73], v[164:167], v[204:207], v[70:73]
	v_mfma_f32_16x16x32_bf16 v[66:69], v[172:175], v[204:207], v[66:69]
	v_mfma_f32_16x16x32_bf16 v[118:121], v[168:171], v[184:187], v[118:121]
	v_mfma_f32_16x16x32_bf16 v[114:117], v[176:179], v[184:187], v[114:117]
	v_mfma_f32_16x16x32_bf16 v[102:105], v[168:171], v[192:195], v[102:105]
	v_mfma_f32_16x16x32_bf16 v[98:101], v[176:179], v[192:195], v[98:101]
	v_mfma_f32_16x16x32_bf16 v[86:89], v[168:171], v[200:203], v[86:89]
	v_mfma_f32_16x16x32_bf16 v[82:85], v[176:179], v[200:203], v[82:85]
	v_mfma_f32_16x16x32_bf16 v[70:73], v[168:171], v[208:211], v[70:73]
	v_mfma_f32_16x16x32_bf16 v[66:69], v[176:179], v[208:211], v[66:69]
	s_setprio 0
	s_barrier
	s_add_i32 s30, s68, s39
	s_mov_b32 m0, s30
	ds_read_b128 v[180:183], v222 offset:49152
	ds_read_b128 v[184:187], v248 offset:49152
	ds_read_b128 v[188:191], v222 offset:51200
	ds_read_b128 v[192:195], v248 offset:51200
	ds_read_b128 v[196:199], v222 offset:53248
	ds_read_b128 v[200:203], v248 offset:53248
	ds_read_b128 v[204:207], v222 offset:55296
	ds_read_b128 v[208:211], v248 offset:55296
	s_add_u32 s98, s28, 0x80
	s_addc_u32 s99, s29, 0
	global_load_lds_dwordx4 v148, s[98:99]
	s_add_i32 m0, s30, 0x2000
	s_add_u32 s28, s28, 0x80080
	s_addc_u32 s29, s29, 0
	s_add_i32 s30, s69, s39
	global_load_lds_dwordx4 v152, s[98:99]
	s_mov_b32 m0, s30
	s_nop 0
	global_load_lds_dwordx4 v148, s[28:29]
	s_add_i32 m0, s30, 0x2000
	s_nop 0
	global_load_lds_dwordx4 v152, s[28:29]
	s_mov_b32 m0, s87
	s_nop 0
	global_load_lds_dwordx4 v146, s[100:101]
	s_mov_b32 m0, s92
	s_nop 0
	global_load_lds_dwordx4 v150, s[100:101]
	s_waitcnt vmcnt(8)
	s_waitcnt lgkmcnt(0)
	s_barrier
	s_setprio 1
	s_waitcnt lgkmcnt(0)
	v_mfma_f32_16x16x32_bf16 v[62:65], v[130:133], v[180:183], v[62:65]
	v_mfma_f32_16x16x32_bf16 v[58:61], v[138:141], v[180:183], v[58:61]
	v_mfma_f32_16x16x32_bf16 v[46:49], v[130:133], v[188:191], v[46:49]
	v_mfma_f32_16x16x32_bf16 v[42:45], v[138:141], v[188:191], v[42:45]
	v_mfma_f32_16x16x32_bf16 v[30:33], v[130:133], v[196:199], v[30:33]
	v_mfma_f32_16x16x32_bf16 v[26:29], v[138:141], v[196:199], v[26:29]
	v_mfma_f32_16x16x32_bf16 v[14:17], v[130:133], v[204:207], v[14:17]
	v_mfma_f32_16x16x32_bf16 v[10:13], v[138:141], v[204:207], v[10:13]
	v_mfma_f32_16x16x32_bf16 v[62:65], v[134:137], v[184:187], v[62:65]
	v_mfma_f32_16x16x32_bf16 v[58:61], v[142:145], v[184:187], v[58:61]
	v_mfma_f32_16x16x32_bf16 v[46:49], v[134:137], v[192:195], v[46:49]
	v_mfma_f32_16x16x32_bf16 v[42:45], v[142:145], v[192:195], v[42:45]
	v_mfma_f32_16x16x32_bf16 v[30:33], v[134:137], v[200:203], v[30:33]
	v_mfma_f32_16x16x32_bf16 v[26:29], v[142:145], v[200:203], v[26:29]
	v_mfma_f32_16x16x32_bf16 v[14:17], v[134:137], v[208:211], v[14:17]
	v_mfma_f32_16x16x32_bf16 v[10:13], v[142:145], v[208:211], v[10:13]
	s_setprio 0
	s_setprio 1
	v_mfma_f32_16x16x32_bf16 v[54:57], v[164:167], v[180:183], v[54:57]
	v_mfma_f32_16x16x32_bf16 v[50:53], v[172:175], v[180:183], v[50:53]
	v_mfma_f32_16x16x32_bf16 v[38:41], v[164:167], v[188:191], v[38:41]
	v_mfma_f32_16x16x32_bf16 v[34:37], v[172:175], v[188:191], v[34:37]
	v_mfma_f32_16x16x32_bf16 v[22:25], v[164:167], v[196:199], v[22:25]
	v_mfma_f32_16x16x32_bf16 v[18:21], v[172:175], v[196:199], v[18:21]
	v_mfma_f32_16x16x32_bf16 v[6:9], v[164:167], v[204:207], v[6:9]
	v_mfma_f32_16x16x32_bf16 v[2:5], v[172:175], v[204:207], v[2:5]
	v_mfma_f32_16x16x32_bf16 v[54:57], v[168:171], v[184:187], v[54:57]
	v_mfma_f32_16x16x32_bf16 v[50:53], v[176:179], v[184:187], v[50:53]
	v_mfma_f32_16x16x32_bf16 v[38:41], v[168:171], v[192:195], v[38:41]
	v_mfma_f32_16x16x32_bf16 v[34:37], v[176:179], v[192:195], v[34:37]
	v_mfma_f32_16x16x32_bf16 v[22:25], v[168:171], v[200:203], v[22:25]
	v_mfma_f32_16x16x32_bf16 v[18:21], v[176:179], v[200:203], v[18:21]
	v_mfma_f32_16x16x32_bf16 v[6:9], v[168:171], v[208:211], v[6:9]
	v_mfma_f32_16x16x32_bf16 v[2:5], v[176:179], v[208:211], v[2:5]
	s_setprio 0
	s_barrier
	s_add_i32 s35, s35, 2
	s_add_u32 s6, s6, 0x100
	s_addc_u32 s7, s7, 0
	s_add_u32 s33, s33, 0x100
	s_addc_u32 s34, s34, 0
	s_cmp_gt_u32 s35, 29
	s_cbranch_scc0 .LBB0_150
	s_and_b64 vcc, exec, s[88:89]
	s_cbranch_vccz .LBB0_153
	s_barrier

.LBB0_974:
	s_cmp_lt_i32 s44, 5
	s_cselect_b64 s[0:1], -1, 0
	s_cmp_gt_i32 s45, 4
	s_cselect_b64 s[2:3], -1, 0
	s_and_b64 s[0:1], s[0:1], s[2:3]
	s_andn2_b64 vcc, exec, s[0:1]
	s_cbranch_vccnz .LBB0_1055
	s_cmpk_gt_i32 s43, 0xff
	v_readfirstlane_b32 s1, v0
	s_cbranch_scc1 .LBB0_1001
	v_lshrrev_b32_e32 v3, 1, v0
	v_and_b32_e32 v13, 24, v3
	v_lshrrev_b32_e32 v3, 5, v0
	s_add_u32 s33, s68, 0x1f400000
	v_lshlrev_b32_e32 v1, 4, v0
	v_and_b32_e32 v2, 32, v0
	v_and_b32_e32 v3, 4, v3
	v_bfe_u32 v4, v0, 2, 2
	s_addc_u32 s38, s69, 0
	v_bfe_u32 v12, v0, 2, 4
	v_bitop3_b32 v10, v1, v2, 48 bitop3:0x6c
	v_and_b32_e32 v11, 64, v0
	v_or3_b32 v3, v3, v4, v13
	v_lshrrev_b32_e32 v4, 3, v0
	v_or_b32_e32 v14, 0x2000, v1
	s_add_u32 s2, s68, 0x3c00000
	v_or_b32_e32 v2, v10, v11
	v_and_or_b32 v5, v4, 48, v12
	v_and_or_b32 v4, v4, 32, v3
	v_lshrrev_b32_e32 v1, 7, v14
	s_movk_i32 s0, 0x70
	s_addc_u32 s3, s69, 0
	v_lshl_or_b32 v132, v4, 12, v2
	v_and_or_b32 v4, v1, s0, v12
	s_movk_i32 s0, 0x60
	s_ashr_i32 s40, s43, 31
	v_and_or_b32 v1, v1, s0, v3
	s_lshr_b32 s0, s40, 29
	s_add_i32 s0, s43, s0
	s_and_b32 s4, s0, -8
	s_lshr_b32 s10, s1, 6
	s_sub_i32 s4, s43, s4
	s_lshr_b32 s12, s1, 8
	s_lshl_b32 s39, s10, 10
	s_lshl_b32 s6, s4, 5
	s_ashr_i32 s0, s0, 3
	s_mul_i32 s5, s4, 33
	s_cmp_lt_i32 s4, 0
	s_cselect_b32 s4, s5, s6
	s_add_i32 s0, s4, s0
	s_ashr_i32 s4, s0, 31
	s_lshr_b32 s4, s4, 27
	s_add_i32 s4, s0, s4
	s_ashr_i32 s5, s4, 5
	s_andn2_b32 s4, s4, 31
	s_sub_i32 s4, s0, s4
	s_bfe_i32 s0, s4, 0x80000
	s_bfe_u32 s0, s0, 0x2000d
	s_add_i32 s6, s4, s0
	s_bfe_i32 s0, s6, 0x80000
	s_and_b32 s6, s6, 0xfc
	s_sub_i32 s4, s4, s6
	s_lshl_b32 s5, s5, 2
	s_sext_i32_i16 s0, s0
	s_sext_i32_i8 s4, s4
	s_lshr_b32 s0, s0, 2
	s_add_i32 s28, s5, s4
	s_ashr_i32 s29, s28, 31
	s_bfe_i64 s[6:7], s[0:1], 0x100000
	s_lshl_b64 s[4:5], s[28:29], 20
	s_lshl_b64 s[6:7], s[6:7], 20
	s_add_u32 s34, s2, s6
	s_addc_u32 s35, s3, s7
	s_add_i32 s29, s39, 0
	s_add_i32 m0, s29, 0x10000
	v_lshl_or_b32 v136, v1, 12, v2
	v_lshrrev_b32_e32 v240, 6, v0
	v_bfe_u32 v241, v0, 3, 3
	v_and_b32_e32 v242, 7, v0
	v_lshrrev_b32_e32 v243, 1, v241
	v_and_b32_e32 v244, 1, v240
	v_lshl_or_b32 v243, v244, 2, v243
	v_xor_b32_e32 v242, v242, v243
	v_lshlrev_b32_e32 v242, 4, v242
	v_lshl_add_u32 v245, v240, 3, v241
	v_lshrrev_b32_e32 v246, 2, v240
	v_lshlrev_b32_e32 v246, 5, v246
	v_lshl_add_u32 v246, v244, 4, v246
	v_lshrrev_b32_e32 v247, 2, v241
	v_lshl_add_u32 v246, v247, 3, v246
	v_bfe_u32 v247, v240, 1, 1
	v_lshl_add_u32 v246, v247, 2, v246
	v_and_b32_e32 v247, 3, v241
	v_add_u32_e32 v246, v246, v247
	v_lshl_add_u32 v130, v245, 12, v242
	v_lshl_add_u32 v132, v246, 12, v242
	v_add_u32_e32 v134, 0x40000, v130
	v_add_u32_e32 v136, 0x40000, v132
	global_load_lds_dwordx4 v132, s[34:35]
	s_add_i32 m0, s29, 0x12000
	s_add_u32 s6, s34, 0x80000
	global_load_lds_dwordx4 v136, s[34:35]
	s_addc_u32 s7, s35, 0
	s_add_i32 m0, s29, 0x14000
	s_nop 0
	global_load_lds_dwordx4 v132, s[6:7]
	s_add_i32 m0, s29, 0x16000
	s_add_u32 s30, s33, s4
	s_addc_u32 s31, s38, s5
	s_add_i32 s41, s29, 0x2000
	global_load_lds_dwordx4 v136, s[6:7]
	s_mov_b32 m0, s29
	s_add_u32 s4, s30, 0x80000
	s_nop 0
	global_load_lds_dwordx4 v130, s[30:31]
	s_mov_b32 m0, s41
	s_addc_u32 s5, s31, 0
	s_add_i32 s42, s29, 0x4000
	global_load_lds_dwordx4 v134, s[30:31]
	s_mov_b32 m0, s42
	s_add_i32 s43, s29, 0x6000
	global_load_lds_dwordx4 v130, s[4:5]
	s_mov_b32 m0, s43
	v_mov_b32_e32 v133, 0
	global_load_lds_dwordx4 v134, s[4:5]
	v_mov_b32_e32 v137, v133
	v_mov_b32_e32 v131, v133
	v_mov_b32_e32 v135, v133
	s_cmp_eq_u32 s12, 1
	s_mov_b32 s44, 0
	v_lshl_add_u64 v[8:9], s[34:35], 0, v[132:133]
	v_lshl_add_u64 v[6:7], s[34:35], 0, v[136:137]
	s_mov_b64 s[6:7], 0x80000
	v_lshl_add_u64 v[2:3], s[30:31], 0, v[130:131]
	s_cselect_b64 s[8:9], -1, 0
	s_cmp_lg_u32 s12, 1
	v_lshl_add_u64 v[4:5], s[30:31], 0, v[134:135]
	s_cbranch_scc1 .LBB0_978
	s_barrier
.LBB0_978:
	s_add_u32 s4, s68, 0x21800000
	s_addc_u32 s5, s69, 0
	v_readlane_b32 s11, v254, 2
	s_lshl_b32 s10, s10, 5
	s_ashr_i32 s45, s11, 31
	s_and_b32 s16, s10, 0x60
	s_mov_b64 s[10:11], 0x80
	s_add_i32 m0, s29, 0x18000
	v_lshl_add_u64 v[8:9], v[8:9], 0, s[10:11]
	s_lshl_b32 s13, s12, 13
	s_lshl_b32 s17, s16, 7
	s_waitcnt vmcnt(2)
	s_barrier
	global_load_lds_dwordx4 v[8:9], off
	v_lshl_add_u64 v[6:7], v[6:7], 0, s[10:11]
	s_add_i32 m0, s29, 0x1a000
	s_add_i32 s46, s29, 0x8000
	s_add_i32 s47, s29, 0xa000
	global_load_lds_dwordx4 v[6:7], off
	v_lshl_add_u64 v[2:3], v[2:3], 0, s[10:11]
	s_mov_b32 m0, s46
	s_add_u32 s14, s34, 0x80080
	global_load_lds_dwordx4 v[2:3], off
	v_lshl_add_u64 v[2:3], v[4:5], 0, s[10:11]
	s_mov_b32 m0, s47
	s_addc_u32 s15, s35, 0
	global_load_lds_dwordx4 v[2:3], off
	s_add_i32 m0, s29, 0x1c000
	v_lshl_add_u64 v[2:3], s[14:15], 0, v[132:133]
	global_load_lds_dwordx4 v[2:3], off
	v_lshl_add_u64 v[2:3], s[14:15], 0, v[136:137]
	s_add_i32 m0, s29, 0x1e000
	s_sext_i32_i8 s54, s0
	global_load_lds_dwordx4 v[2:3], off
	v_lshlrev_b32_e32 v3, 1, v13
	v_lshlrev_b32_e32 v1, 6, v0
	s_movk_i32 s0, 0x3c0
	v_and_b32_e32 v2, 15, v0
	v_and_or_b32 v4, v1, s0, v3
	v_lshlrev_b32_e32 v1, 2, v0
	v_and_b32_e32 v5, 32, v1
	v_lshl_or_b32 v1, s12, 6, v2
	v_lshl_or_b32 v2, v2, 6, v3
	v_lshlrev_b32_e32 v3, 9, v0
	v_bitop3_b32 v146, s17, v4, v5 bitop3:0xf6
	v_and_b32_e32 v3, 0x30000, v3
	v_lshlrev_b32_e32 v4, 12, v12
	v_or3_b32 v3, v10, v3, v4
	v_add_u32_e32 v138, v3, v11
	v_lshlrev_b32_e32 v3, 5, v14
	s_waitcnt vmcnt(6)
	s_cmpk_lt_u32 s1, 0x100
	v_and_b32_e32 v3, 0x70000, v3
	v_bitop3_b32 v2, v2, s13, v5 bitop3:0xde
	s_cselect_b64 s[12:13], -1, 0
	v_or3_b32 v3, v10, v3, v4
	s_add_i32 s48, 0, 0x10000
	s_add_i32 s49, 0, 0x14000
	v_or_b32_e32 v147, s16, v13
	v_mov_b32_e32 v139, v133
	v_add_u32_e32 v140, v3, v11
	v_mov_b32_e32 v141, v133
	v_mov_b64_e32 v[142:143], 0x100
	v_mov_b64_e32 v[144:145], 0xff
	v_add_u32_e32 v148, s48, v146
	v_add_u32_e32 v149, s49, v146
	v_add_u32_e32 v150, 0, v2
	s_mov_b32 s50, 0x80000
	s_mov_b64 s[14:15], 0x90000
	s_mov_b32 s51, 0x90000
	s_mov_b64 s[16:17], 0xa0000
	s_mov_b32 s52, 0xa0000
	s_mov_b64 s[18:19], 0xb0000
	s_mov_b32 s53, 0xb0000
	s_barrier
	v_mov_b32_e32 v138, v130
	v_mov_b32_e32 v140, v134
	v_and_b32_e32 v240, 63, v0
	v_and_b32_e32 v241, 15, v240
	v_lshrrev_b32_e32 v242, 4, v240
	v_lshrrev_b32_e32 v243, 3, v241
	v_lshlrev_b32_e32 v243, 10, v243
	v_and_b32_e32 v244, 7, v241
	v_lshl_add_u32 v243, v244, 7, v243
	v_lshrrev_b32_e32 v244, 1, v241
	v_xor_b32_e32 v245, v242, v244
	v_lshl_add_u32 v245, v245, 4, v243
	v_xor_b32_e32 v246, 64, v245
	v_lshrrev_b32_e32 v247, 6, v0
	v_lshrrev_b32_e32 v244, 2, v247
	v_lshl_add_u32 v150, v244, 13, v245
	v_lshl_add_u32 v248, v244, 13, v246
	v_and_b32_e32 v244, 3, v247
	v_lshl_add_u32 v146, v244, 12, v245
	v_lshl_add_u32 v249, v244, 12, v246
	v_add_u32_e32 v148, s48, v146
	v_add_u32_e32 v250, s48, v249
	v_add_u32_e32 v149, s49, v146
	v_add_u32_e32 v251, s49, v249
	s_branch .LBB0_981

.LBB0_988:
	ds_read_b128 v[152:155], v148
	ds_read_b128 v[156:159], v250
	ds_read_b128 v[160:163], v148 offset:2048
	ds_read_b128 v[164:167], v250 offset:2048
	ds_read_b128 v[168:171], v149
	ds_read_b128 v[172:175], v251
	ds_read_b128 v[176:179], v149 offset:2048
	ds_read_b128 v[180:183], v251 offset:2048
	s_add_u32 s34, s30, 0xfff80080
	s_addc_u32 s35, s31, -1
	s_cmp_eq_u32 s59, 28
	s_cselect_b32 s37, s23, s35
	s_cselect_b32 s36, s55, s34
	s_cselect_b32 s35, s21, s58
	s_cselect_b32 s34, s56, s57
	s_add_i32 m0, s29, 0xc000
	ds_read_b128 v[184:187], v150
	ds_read_b128 v[188:191], v248
	ds_read_b128 v[192:195], v150 offset:2048
	ds_read_b128 v[196:199], v248 offset:2048
	ds_read_b128 v[200:203], v150 offset:4096
	ds_read_b128 v[204:207], v248 offset:4096
	ds_read_b128 v[208:211], v150 offset:6144
	ds_read_b128 v[212:215], v248 offset:6144
	global_load_lds_dwordx4 v138, s[30:31]
	s_add_i32 m0, s29, 0xe000
	s_nop 0
	global_load_lds_dwordx4 v140, s[30:31]
	s_waitcnt vmcnt(8)
	s_waitcnt lgkmcnt(0)
	s_barrier
	s_setprio 1
	s_waitcnt lgkmcnt(0)
	v_mfma_f32_16x16x32_bf16 v[126:129], v[152:155], v[184:187], v[126:129]
	v_mfma_f32_16x16x32_bf16 v[122:125], v[160:163], v[184:187], v[122:125]
	v_mfma_f32_16x16x32_bf16 v[118:121], v[152:155], v[192:195], v[118:121]
	v_mfma_f32_16x16x32_bf16 v[110:113], v[160:163], v[192:195], v[110:113]
	v_mfma_f32_16x16x32_bf16 v[102:105], v[152:155], v[200:203], v[102:105]
	v_mfma_f32_16x16x32_bf16 v[94:97], v[160:163], v[200:203], v[94:97]
	v_mfma_f32_16x16x32_bf16 v[86:89], v[152:155], v[208:211], v[86:89]
	v_mfma_f32_16x16x32_bf16 v[78:81], v[160:163], v[208:211], v[78:81]
	v_mfma_f32_16x16x32_bf16 v[126:129], v[156:159], v[188:191], v[126:129]
	v_mfma_f32_16x16x32_bf16 v[122:125], v[164:167], v[188:191], v[122:125]
	v_mfma_f32_16x16x32_bf16 v[118:121], v[156:159], v[196:199], v[118:121]
	v_mfma_f32_16x16x32_bf16 v[110:113], v[164:167], v[196:199], v[110:113]
	v_mfma_f32_16x16x32_bf16 v[102:105], v[156:159], v[204:207], v[102:105]
	v_mfma_f32_16x16x32_bf16 v[94:97], v[164:167], v[204:207], v[94:97]
	v_mfma_f32_16x16x32_bf16 v[86:89], v[156:159], v[212:215], v[86:89]
	v_mfma_f32_16x16x32_bf16 v[78:81], v[164:167], v[212:215], v[78:81]
	s_setprio 0
	s_setprio 1
	v_mfma_f32_16x16x32_bf16 v[114:117], v[168:171], v[184:187], v[114:117]
	v_mfma_f32_16x16x32_bf16 v[106:109], v[176:179], v[184:187], v[106:109]
	v_mfma_f32_16x16x32_bf16 v[98:101], v[168:171], v[192:195], v[98:101]
	v_mfma_f32_16x16x32_bf16 v[90:93], v[176:179], v[192:195], v[90:93]
	v_mfma_f32_16x16x32_bf16 v[82:85], v[168:171], v[200:203], v[82:85]
	v_mfma_f32_16x16x32_bf16 v[74:77], v[176:179], v[200:203], v[74:77]
	v_mfma_f32_16x16x32_bf16 v[70:73], v[168:171], v[208:211], v[70:73]
	v_mfma_f32_16x16x32_bf16 v[66:69], v[176:179], v[208:211], v[66:69]
	v_mfma_f32_16x16x32_bf16 v[114:117], v[172:175], v[188:191], v[114:117]
	v_mfma_f32_16x16x32_bf16 v[106:109], v[180:183], v[188:191], v[106:109]
	v_mfma_f32_16x16x32_bf16 v[98:101], v[172:175], v[196:199], v[98:101]
	v_mfma_f32_16x16x32_bf16 v[90:93], v[180:183], v[196:199], v[90:93]
	v_mfma_f32_16x16x32_bf16 v[82:85], v[172:175], v[204:207], v[82:85]
	v_mfma_f32_16x16x32_bf16 v[74:77], v[180:183], v[204:207], v[74:77]
	v_mfma_f32_16x16x32_bf16 v[70:73], v[172:175], v[212:215], v[70:73]
	v_mfma_f32_16x16x32_bf16 v[66:69], v[180:183], v[212:215], v[66:69]
	s_setprio 0
	s_barrier
	s_add_i32 s60, s48, s39
	s_mov_b32 m0, s60
	ds_read_b128 v[184:187], v150 offset:16384
	ds_read_b128 v[188:191], v248 offset:16384
	ds_read_b128 v[192:195], v150 offset:18432
	ds_read_b128 v[196:199], v248 offset:18432
	ds_read_b128 v[200:203], v150 offset:20480
	ds_read_b128 v[204:207], v248 offset:20480
	ds_read_b128 v[208:211], v150 offset:22528
	ds_read_b128 v[212:215], v248 offset:22528
	global_load_lds_dwordx4 v132, s[34:35]
	s_add_i32 m0, s60, 0x2000
	s_add_u32 s60, s34, 0x80000
	s_addc_u32 s61, s35, 0
	s_add_i32 s62, s49, s39
	global_load_lds_dwordx4 v136, s[34:35]
	s_mov_b32 m0, s62
	s_nop 0
	global_load_lds_dwordx4 v132, s[60:61]
	s_add_i32 m0, s62, 0x2000
	s_nop 0
	global_load_lds_dwordx4 v136, s[60:61]
	s_mov_b32 m0, s29
	s_nop 0
	global_load_lds_dwordx4 v130, s[36:37]
	s_mov_b32 m0, s41
	s_nop 0
	global_load_lds_dwordx4 v134, s[36:37]
	s_waitcnt vmcnt(8)
	s_waitcnt lgkmcnt(0)
	s_barrier
	s_setprio 1
	s_waitcnt lgkmcnt(0)
	v_mfma_f32_16x16x32_bf16 v[62:65], v[152:155], v[184:187], v[62:65]
	v_mfma_f32_16x16x32_bf16 v[58:61], v[160:163], v[184:187], v[58:61]
	v_mfma_f32_16x16x32_bf16 v[54:57], v[152:155], v[192:195], v[54:57]
	v_mfma_f32_16x16x32_bf16 v[46:49], v[160:163], v[192:195], v[46:49]
	v_mfma_f32_16x16x32_bf16 v[38:41], v[152:155], v[200:203], v[38:41]
	v_mfma_f32_16x16x32_bf16 v[30:33], v[160:163], v[200:203], v[30:33]
	v_mfma_f32_16x16x32_bf16 v[22:25], v[152:155], v[208:211], v[22:25]
	v_mfma_f32_16x16x32_bf16 v[14:17], v[160:163], v[208:211], v[14:17]
	v_mfma_f32_16x16x32_bf16 v[62:65], v[156:159], v[188:191], v[62:65]
	v_mfma_f32_16x16x32_bf16 v[58:61], v[164:167], v[188:191], v[58:61]
	v_mfma_f32_16x16x32_bf16 v[54:57], v[156:159], v[196:199], v[54:57]
	v_mfma_f32_16x16x32_bf16 v[46:49], v[164:167], v[196:199], v[46:49]
	v_mfma_f32_16x16x32_bf16 v[38:41], v[156:159], v[204:207], v[38:41]
	v_mfma_f32_16x16x32_bf16 v[30:33], v[164:167], v[204:207], v[30:33]
	v_mfma_f32_16x16x32_bf16 v[22:25], v[156:159], v[212:215], v[22:25]
	v_mfma_f32_16x16x32_bf16 v[14:17], v[164:167], v[212:215], v[14:17]
	s_setprio 0
	s_setprio 1
	v_mfma_f32_16x16x32_bf16 v[50:53], v[168:171], v[184:187], v[50:53]
	v_mfma_f32_16x16x32_bf16 v[42:45], v[176:179], v[184:187], v[42:45]
	v_mfma_f32_16x16x32_bf16 v[34:37], v[168:171], v[192:195], v[34:37]
	v_mfma_f32_16x16x32_bf16 v[26:29], v[176:179], v[192:195], v[26:29]
	v_mfma_f32_16x16x32_bf16 v[18:21], v[168:171], v[200:203], v[18:21]
	v_mfma_f32_16x16x32_bf16 v[10:13], v[176:179], v[200:203], v[10:13]
	v_mfma_f32_16x16x32_bf16 v[6:9], v[168:171], v[208:211], v[6:9]
	v_mfma_f32_16x16x32_bf16 v[2:5], v[176:179], v[208:211], v[2:5]
	v_mfma_f32_16x16x32_bf16 v[50:53], v[172:175], v[188:191], v[50:53]
	v_mfma_f32_16x16x32_bf16 v[42:45], v[180:183], v[188:191], v[42:45]
	v_mfma_f32_16x16x32_bf16 v[34:37], v[172:175], v[196:199], v[34:37]
	v_mfma_f32_16x16x32_bf16 v[26:29], v[180:183], v[196:199], v[26:29]
	v_mfma_f32_16x16x32_bf16 v[18:21], v[172:175], v[204:207], v[18:21]
	v_mfma_f32_16x16x32_bf16 v[10:13], v[180:183], v[204:207], v[10:13]
	v_mfma_f32_16x16x32_bf16 v[6:9], v[172:175], v[212:215], v[6:9]
	v_mfma_f32_16x16x32_bf16 v[2:5], v[180:183], v[212:215], v[2:5]
	s_setprio 0
	s_barrier
	s_add_i32 s60, 0, 0x18000
	v_add_u32_e32 v151, s60, v146
	v_add_u32_e32 v252, s60, v249
	s_add_i32 s61, 0, 0x1c000
	ds_read_b128 v[152:155], v151
	ds_read_b128 v[156:159], v252
	ds_read_b128 v[160:163], v151 offset:2048
	ds_read_b128 v[164:167], v252 offset:2048
	v_add_u32_e32 v151, s61, v146
	v_add_u32_e32 v253, s61, v249
	ds_read_b128 v[168:171], v151
	ds_read_b128 v[172:175], v253
	ds_read_b128 v[176:179], v151 offset:2048
	ds_read_b128 v[180:183], v253 offset:2048
	s_add_u32 s36, s36, 0x80000
	s_addc_u32 s37, s37, 0
	s_add_u32 s100, s36, 0xfff80080
	s_addc_u32 s101, s37, -1
	s_mov_b32 m0, s42
	ds_read_b128 v[184:187], v150 offset:32768
	ds_read_b128 v[188:191], v248 offset:32768
	ds_read_b128 v[192:195], v150 offset:34816
	ds_read_b128 v[196:199], v248 offset:34816
	ds_read_b128 v[200:203], v150 offset:36864
	ds_read_b128 v[204:207], v248 offset:36864
	ds_read_b128 v[208:211], v150 offset:38912
	ds_read_b128 v[212:215], v248 offset:38912
	global_load_lds_dwordx4 v130, s[36:37]
	s_mov_b32 m0, s43
	s_nop 0
	global_load_lds_dwordx4 v134, s[36:37]
	s_waitcnt vmcnt(8)
	s_waitcnt lgkmcnt(0)
	s_barrier
	s_setprio 1
	s_waitcnt lgkmcnt(0)
	v_mfma_f32_16x16x32_bf16 v[126:129], v[152:155], v[184:187], v[126:129]
	v_mfma_f32_16x16x32_bf16 v[122:125], v[160:163], v[184:187], v[122:125]
	v_mfma_f32_16x16x32_bf16 v[118:121], v[152:155], v[192:195], v[118:121]
	v_mfma_f32_16x16x32_bf16 v[110:113], v[160:163], v[192:195], v[110:113]
	v_mfma_f32_16x16x32_bf16 v[102:105], v[152:155], v[200:203], v[102:105]
	v_mfma_f32_16x16x32_bf16 v[94:97], v[160:163], v[200:203], v[94:97]
	v_mfma_f32_16x16x32_bf16 v[86:89], v[152:155], v[208:211], v[86:89]
	v_mfma_f32_16x16x32_bf16 v[78:81], v[160:163], v[208:211], v[78:81]
	v_mfma_f32_16x16x32_bf16 v[126:129], v[156:159], v[188:191], v[126:129]
	v_mfma_f32_16x16x32_bf16 v[122:125], v[164:167], v[188:191], v[122:125]
	v_mfma_f32_16x16x32_bf16 v[118:121], v[156:159], v[196:199], v[118:121]
	v_mfma_f32_16x16x32_bf16 v[110:113], v[164:167], v[196:199], v[110:113]
	v_mfma_f32_16x16x32_bf16 v[102:105], v[156:159], v[204:207], v[102:105]
	v_mfma_f32_16x16x32_bf16 v[94:97], v[164:167], v[204:207], v[94:97]
	v_mfma_f32_16x16x32_bf16 v[86:89], v[156:159], v[212:215], v[86:89]
	v_mfma_f32_16x16x32_bf16 v[78:81], v[164:167], v[212:215], v[78:81]
	s_setprio 0
	s_setprio 1
	v_mfma_f32_16x16x32_bf16 v[114:117], v[168:171], v[184:187], v[114:117]
	v_mfma_f32_16x16x32_bf16 v[106:109], v[176:179], v[184:187], v[106:109]
	v_mfma_f32_16x16x32_bf16 v[98:101], v[168:171], v[192:195], v[98:101]
	v_mfma_f32_16x16x32_bf16 v[90:93], v[176:179], v[192:195], v[90:93]
	v_mfma_f32_16x16x32_bf16 v[82:85], v[168:171], v[200:203], v[82:85]
	v_mfma_f32_16x16x32_bf16 v[74:77], v[176:179], v[200:203], v[74:77]
	v_mfma_f32_16x16x32_bf16 v[70:73], v[168:171], v[208:211], v[70:73]
	v_mfma_f32_16x16x32_bf16 v[66:69], v[176:179], v[208:211], v[66:69]
	v_mfma_f32_16x16x32_bf16 v[114:117], v[172:175], v[188:191], v[114:117]
	v_mfma_f32_16x16x32_bf16 v[106:109], v[180:183], v[188:191], v[106:109]
	v_mfma_f32_16x16x32_bf16 v[98:101], v[172:175], v[196:199], v[98:101]
	v_mfma_f32_16x16x32_bf16 v[90:93], v[180:183], v[196:199], v[90:93]
	v_mfma_f32_16x16x32_bf16 v[82:85], v[172:175], v[204:207], v[82:85]
	v_mfma_f32_16x16x32_bf16 v[74:77], v[180:183], v[204:207], v[74:77]
	v_mfma_f32_16x16x32_bf16 v[70:73], v[172:175], v[212:215], v[70:73]
	v_mfma_f32_16x16x32_bf16 v[66:69], v[180:183], v[212:215], v[66:69]
	s_setprio 0
	s_barrier
	s_add_i32 s36, s60, s39
	s_mov_b32 m0, s36
	ds_read_b128 v[184:187], v150 offset:49152
	ds_read_b128 v[188:191], v248 offset:49152
	ds_read_b128 v[192:195], v150 offset:51200
	ds_read_b128 v[196:199], v248 offset:51200
	ds_read_b128 v[200:203], v150 offset:53248
	ds_read_b128 v[204:207], v248 offset:53248
	ds_read_b128 v[208:211], v150 offset:55296
	ds_read_b128 v[212:215], v248 offset:55296
	s_add_u32 s98, s34, 0x80
	s_addc_u32 s99, s35, 0
	global_load_lds_dwordx4 v132, s[98:99]
	s_add_i32 m0, s36, 0x2000
	s_add_u32 s34, s34, 0x80080
	s_addc_u32 s35, s35, 0
	s_add_i32 s36, s61, s39
	global_load_lds_dwordx4 v136, s[98:99]
	s_mov_b32 m0, s36
	s_nop 0
	global_load_lds_dwordx4 v132, s[34:35]
	s_add_i32 m0, s36, 0x2000
	s_nop 0
	global_load_lds_dwordx4 v136, s[34:35]
	s_mov_b32 m0, s46
	s_nop 0
	global_load_lds_dwordx4 v130, s[100:101]
	s_mov_b32 m0, s47
	s_nop 0
	global_load_lds_dwordx4 v134, s[100:101]
	s_waitcnt vmcnt(8)
	s_waitcnt lgkmcnt(0)
	s_barrier
	s_setprio 1
	s_waitcnt lgkmcnt(0)
	v_mfma_f32_16x16x32_bf16 v[62:65], v[152:155], v[184:187], v[62:65]
	v_mfma_f32_16x16x32_bf16 v[58:61], v[160:163], v[184:187], v[58:61]
	v_mfma_f32_16x16x32_bf16 v[54:57], v[152:155], v[192:195], v[54:57]
	v_mfma_f32_16x16x32_bf16 v[46:49], v[160:163], v[192:195], v[46:49]
	v_mfma_f32_16x16x32_bf16 v[38:41], v[152:155], v[200:203], v[38:41]
	v_mfma_f32_16x16x32_bf16 v[30:33], v[160:163], v[200:203], v[30:33]
	v_mfma_f32_16x16x32_bf16 v[22:25], v[152:155], v[208:211], v[22:25]
	v_mfma_f32_16x16x32_bf16 v[14:17], v[160:163], v[208:211], v[14:17]
	v_mfma_f32_16x16x32_bf16 v[62:65], v[156:159], v[188:191], v[62:65]
	v_mfma_f32_16x16x32_bf16 v[58:61], v[164:167], v[188:191], v[58:61]
	v_mfma_f32_16x16x32_bf16 v[54:57], v[156:159], v[196:199], v[54:57]
	v_mfma_f32_16x16x32_bf16 v[46:49], v[164:167], v[196:199], v[46:49]
	v_mfma_f32_16x16x32_bf16 v[38:41], v[156:159], v[204:207], v[38:41]
	v_mfma_f32_16x16x32_bf16 v[30:33], v[164:167], v[204:207], v[30:33]
	v_mfma_f32_16x16x32_bf16 v[22:25], v[156:159], v[212:215], v[22:25]
	v_mfma_f32_16x16x32_bf16 v[14:17], v[164:167], v[212:215], v[14:17]
	s_setprio 0
	s_setprio 1
	v_mfma_f32_16x16x32_bf16 v[50:53], v[168:171], v[184:187], v[50:53]
	v_mfma_f32_16x16x32_bf16 v[42:45], v[176:179], v[184:187], v[42:45]
	v_mfma_f32_16x16x32_bf16 v[34:37], v[168:171], v[192:195], v[34:37]
	v_mfma_f32_16x16x32_bf16 v[26:29], v[176:179], v[192:195], v[26:29]
	v_mfma_f32_16x16x32_bf16 v[18:21], v[168:171], v[200:203], v[18:21]
	v_mfma_f32_16x16x32_bf16 v[10:13], v[176:179], v[200:203], v[10:13]
	v_mfma_f32_16x16x32_bf16 v[6:9], v[168:171], v[208:211], v[6:9]
	v_mfma_f32_16x16x32_bf16 v[2:5], v[176:179], v[208:211], v[2:5]
	v_mfma_f32_16x16x32_bf16 v[50:53], v[172:175], v[188:191], v[50:53]
	v_mfma_f32_16x16x32_bf16 v[42:45], v[180:183], v[188:191], v[42:45]
	v_mfma_f32_16x16x32_bf16 v[34:37], v[172:175], v[196:199], v[34:37]
	v_mfma_f32_16x16x32_bf16 v[26:29], v[180:183], v[196:199], v[26:29]
	v_mfma_f32_16x16x32_bf16 v[18:21], v[172:175], v[204:207], v[18:21]
	v_mfma_f32_16x16x32_bf16 v[10:13], v[180:183], v[204:207], v[10:13]
	v_mfma_f32_16x16x32_bf16 v[6:9], v[172:175], v[212:215], v[6:9]
	v_mfma_f32_16x16x32_bf16 v[2:5], v[180:183], v[212:215], v[2:5]
	s_setprio 0
	s_barrier
	s_add_i32 s59, s59, 2
	s_add_u32 s30, s30, 0x100
	s_addc_u32 s31, s31, 0
	s_add_u32 s57, s57, 0x100
	s_addc_u32 s58, s58, 0
	s_cmp_gt_u32 s59, 29
	s_cbranch_scc0 .LBB0_988
	s_and_b64 vcc, exec, s[12:13]
	s_cbranch_vccz .LBB0_991
	s_barrier

.LBB0_1125:
	s_add_u32 s4, s68, 0x2c400000
	s_addc_u32 s5, s69, 0
	v_readlane_b32 s7, v254, 2
	s_lshl_b32 s6, s6, 5
	s_ashr_i32 s37, s7, 31
	s_and_b32 s12, s6, 0x60
	s_mov_b64 s[6:7], 0x80
	s_add_i32 m0, s19, 0x18000
	v_lshl_add_u64 v[8:9], v[8:9], 0, s[6:7]
	s_lshl_b32 s9, s8, 13
	s_lshl_b32 s13, s12, 7
	s_waitcnt vmcnt(2)
	s_barrier
	global_load_lds_dwordx4 v[8:9], off
	v_lshl_add_u64 v[6:7], v[6:7], 0, s[6:7]
	s_add_i32 m0, s19, 0x1a000
	s_add_i32 s38, s19, 0x8000
	s_add_i32 s39, s19, 0xa000
	global_load_lds_dwordx4 v[6:7], off
	v_lshl_add_u64 v[2:3], v[2:3], 0, s[6:7]
	s_mov_b32 m0, s38
	s_add_u32 s10, s22, 0x80080
	global_load_lds_dwordx4 v[2:3], off
	v_lshl_add_u64 v[2:3], v[4:5], 0, s[6:7]
	s_mov_b32 m0, s39
	s_addc_u32 s11, s23, 0
	global_load_lds_dwordx4 v[2:3], off
	s_add_i32 m0, s19, 0x1c000
	v_lshl_add_u64 v[2:3], s[10:11], 0, v[132:133]
	global_load_lds_dwordx4 v[2:3], off
	v_lshl_add_u64 v[2:3], s[10:11], 0, v[136:137]
	s_add_i32 m0, s19, 0x1e000
	s_sext_i32_i16 s43, s0
	global_load_lds_dwordx4 v[2:3], off
	v_and_b32_e32 v2, 15, v0
	v_lshlrev_b32_e32 v3, 1, v13
	v_lshlrev_b32_e32 v4, 6, v0
	s_movk_i32 s0, 0x3c0
	v_and_or_b32 v4, v4, s0, v3
	v_and_b32_e32 v5, 32, v1
	v_lshl_or_b32 v146, s8, 6, v2
	v_lshl_or_b32 v2, v2, 6, v3
	v_lshlrev_b32_e32 v3, 9, v0
	v_bitop3_b32 v147, s13, v4, v5 bitop3:0xf6
	v_and_b32_e32 v3, 0x30000, v3
	v_lshlrev_b32_e32 v4, 12, v12
	v_or3_b32 v3, v10, v3, v4
	v_add_u32_e32 v138, v3, v11
	v_lshlrev_b32_e32 v3, 5, v14
	s_waitcnt vmcnt(6)
	s_cmpk_lt_u32 s1, 0x100
	v_and_b32_e32 v3, 0x70000, v3
	v_bitop3_b32 v2, v2, s9, v5 bitop3:0xde
	s_cselect_b64 s[8:9], -1, 0
	v_or3_b32 v3, v10, v3, v4
	s_add_i32 s40, 0, 0x10000
	s_add_i32 s41, 0, 0x14000
	v_or_b32_e32 v148, s12, v13
	v_mov_b32_e32 v139, v133
	v_add_u32_e32 v140, v3, v11
	v_mov_b32_e32 v141, v133
	v_mov_b64_e32 v[142:143], 0x5ac
	v_mov_b64_e32 v[144:145], 0x5ab
	v_add_u32_e32 v149, s40, v147
	v_add_u32_e32 v150, s41, v147
	v_add_u32_e32 v151, 0, v2
	s_movk_i32 s42, 0x2c00
	s_barrier
	v_mov_b32_e32 v138, v130
	v_mov_b32_e32 v140, v134
	v_and_b32_e32 v240, 63, v0
	v_and_b32_e32 v241, 15, v240
	v_lshrrev_b32_e32 v242, 4, v240
	v_lshrrev_b32_e32 v243, 3, v241
	v_lshlrev_b32_e32 v243, 10, v243
	v_and_b32_e32 v244, 7, v241
	v_lshl_add_u32 v243, v244, 7, v243
	v_lshrrev_b32_e32 v244, 1, v241
	v_xor_b32_e32 v245, v242, v244
	v_lshl_add_u32 v245, v245, 4, v243
	v_xor_b32_e32 v246, 64, v245
	v_lshrrev_b32_e32 v247, 6, v0
	v_lshrrev_b32_e32 v244, 2, v247
	v_lshl_add_u32 v151, v244, 13, v245
	v_lshl_add_u32 v248, v244, 13, v246
	v_and_b32_e32 v244, 3, v247
	v_lshl_add_u32 v147, v244, 12, v245
	v_lshl_add_u32 v249, v244, 12, v246
	v_add_u32_e32 v149, s40, v147
	v_add_u32_e32 v250, s40, v249
	v_add_u32_e32 v150, s41, v147
	v_add_u32_e32 v251, s41, v249
	s_branch .LBB0_1128

.LBB0_1135:
	ds_read_b128 v[152:155], v149
	ds_read_b128 v[156:159], v250
	ds_read_b128 v[160:163], v149 offset:2048
	ds_read_b128 v[164:167], v250 offset:2048
	ds_read_b128 v[168:171], v150
	ds_read_b128 v[172:175], v251
	ds_read_b128 v[176:179], v150 offset:2048
	ds_read_b128 v[180:183], v251 offset:2048
	s_add_u32 s22, s20, 0xfff80080
	s_addc_u32 s23, s21, -1
	s_cmp_eq_u32 s48, 28
	s_cselect_b32 s25, s13, s23
	s_cselect_b32 s24, s44, s22
	s_cselect_b32 s23, s11, s47
	s_cselect_b32 s22, s45, s46
	s_add_i32 m0, s19, 0xc000
	ds_read_b128 v[184:187], v151
	ds_read_b128 v[188:191], v248
	ds_read_b128 v[192:195], v151 offset:2048
	ds_read_b128 v[196:199], v248 offset:2048
	ds_read_b128 v[200:203], v151 offset:4096
	ds_read_b128 v[204:207], v248 offset:4096
	ds_read_b128 v[208:211], v151 offset:6144
	ds_read_b128 v[212:215], v248 offset:6144
	global_load_lds_dwordx4 v138, s[20:21]
	s_add_i32 m0, s19, 0xe000
	s_nop 0
	global_load_lds_dwordx4 v140, s[20:21]
	s_waitcnt vmcnt(8)
	s_waitcnt lgkmcnt(0)
	s_barrier
	s_setprio 1
	s_waitcnt lgkmcnt(0)
	v_mfma_f32_16x16x32_bf16 v[126:129], v[152:155], v[184:187], v[126:129]
	v_mfma_f32_16x16x32_bf16 v[122:125], v[160:163], v[184:187], v[122:125]
	v_mfma_f32_16x16x32_bf16 v[110:113], v[152:155], v[192:195], v[110:113]
	v_mfma_f32_16x16x32_bf16 v[106:109], v[160:163], v[192:195], v[106:109]
	v_mfma_f32_16x16x32_bf16 v[94:97], v[152:155], v[200:203], v[94:97]
	v_mfma_f32_16x16x32_bf16 v[90:93], v[160:163], v[200:203], v[90:93]
	v_mfma_f32_16x16x32_bf16 v[78:81], v[152:155], v[208:211], v[78:81]
	v_mfma_f32_16x16x32_bf16 v[74:77], v[160:163], v[208:211], v[74:77]
	v_mfma_f32_16x16x32_bf16 v[126:129], v[156:159], v[188:191], v[126:129]
	v_mfma_f32_16x16x32_bf16 v[122:125], v[164:167], v[188:191], v[122:125]
	v_mfma_f32_16x16x32_bf16 v[110:113], v[156:159], v[196:199], v[110:113]
	v_mfma_f32_16x16x32_bf16 v[106:109], v[164:167], v[196:199], v[106:109]
	v_mfma_f32_16x16x32_bf16 v[94:97], v[156:159], v[204:207], v[94:97]
	v_mfma_f32_16x16x32_bf16 v[90:93], v[164:167], v[204:207], v[90:93]
	v_mfma_f32_16x16x32_bf16 v[78:81], v[156:159], v[212:215], v[78:81]
	v_mfma_f32_16x16x32_bf16 v[74:77], v[164:167], v[212:215], v[74:77]
	s_setprio 0
	s_setprio 1
	v_mfma_f32_16x16x32_bf16 v[118:121], v[168:171], v[184:187], v[118:121]
	v_mfma_f32_16x16x32_bf16 v[114:117], v[176:179], v[184:187], v[114:117]
	v_mfma_f32_16x16x32_bf16 v[102:105], v[168:171], v[192:195], v[102:105]
	v_mfma_f32_16x16x32_bf16 v[98:101], v[176:179], v[192:195], v[98:101]
	v_mfma_f32_16x16x32_bf16 v[86:89], v[168:171], v[200:203], v[86:89]
	v_mfma_f32_16x16x32_bf16 v[82:85], v[176:179], v[200:203], v[82:85]
	v_mfma_f32_16x16x32_bf16 v[70:73], v[168:171], v[208:211], v[70:73]
	v_mfma_f32_16x16x32_bf16 v[66:69], v[176:179], v[208:211], v[66:69]
	v_mfma_f32_16x16x32_bf16 v[118:121], v[172:175], v[188:191], v[118:121]
	v_mfma_f32_16x16x32_bf16 v[114:117], v[180:183], v[188:191], v[114:117]
	v_mfma_f32_16x16x32_bf16 v[102:105], v[172:175], v[196:199], v[102:105]
	v_mfma_f32_16x16x32_bf16 v[98:101], v[180:183], v[196:199], v[98:101]
	v_mfma_f32_16x16x32_bf16 v[86:89], v[172:175], v[204:207], v[86:89]
	v_mfma_f32_16x16x32_bf16 v[82:85], v[180:183], v[204:207], v[82:85]
	v_mfma_f32_16x16x32_bf16 v[70:73], v[172:175], v[212:215], v[70:73]
	v_mfma_f32_16x16x32_bf16 v[66:69], v[180:183], v[212:215], v[66:69]
	s_setprio 0
	s_barrier
	s_add_i32 s49, s40, s30
	s_mov_b32 m0, s49
	ds_read_b128 v[184:187], v151 offset:16384
	ds_read_b128 v[188:191], v248 offset:16384
	ds_read_b128 v[192:195], v151 offset:18432
	ds_read_b128 v[196:199], v248 offset:18432
	ds_read_b128 v[200:203], v151 offset:20480
	ds_read_b128 v[204:207], v248 offset:20480
	ds_read_b128 v[208:211], v151 offset:22528
	ds_read_b128 v[212:215], v248 offset:22528
	global_load_lds_dwordx4 v132, s[22:23]
	s_add_i32 m0, s49, 0x2000
	s_add_u32 s50, s22, 0x80000
	s_addc_u32 s51, s23, 0
	s_add_i32 s49, s41, s30
	global_load_lds_dwordx4 v136, s[22:23]
	s_mov_b32 m0, s49
	s_nop 0
	global_load_lds_dwordx4 v132, s[50:51]
	s_add_i32 m0, s49, 0x2000
	s_nop 0
	global_load_lds_dwordx4 v136, s[50:51]
	s_mov_b32 m0, s19
	s_nop 0
	global_load_lds_dwordx4 v130, s[24:25]
	s_mov_b32 m0, s33
	s_nop 0
	global_load_lds_dwordx4 v134, s[24:25]
	s_waitcnt vmcnt(8)
	s_waitcnt lgkmcnt(0)
	s_barrier
	s_setprio 1
	s_waitcnt lgkmcnt(0)
	v_mfma_f32_16x16x32_bf16 v[62:65], v[152:155], v[184:187], v[62:65]
	v_mfma_f32_16x16x32_bf16 v[58:61], v[160:163], v[184:187], v[58:61]
	v_mfma_f32_16x16x32_bf16 v[46:49], v[152:155], v[192:195], v[46:49]
	v_mfma_f32_16x16x32_bf16 v[42:45], v[160:163], v[192:195], v[42:45]
	v_mfma_f32_16x16x32_bf16 v[30:33], v[152:155], v[200:203], v[30:33]
	v_mfma_f32_16x16x32_bf16 v[26:29], v[160:163], v[200:203], v[26:29]
	v_mfma_f32_16x16x32_bf16 v[14:17], v[152:155], v[208:211], v[14:17]
	v_mfma_f32_16x16x32_bf16 v[10:13], v[160:163], v[208:211], v[10:13]
	v_mfma_f32_16x16x32_bf16 v[62:65], v[156:159], v[188:191], v[62:65]
	v_mfma_f32_16x16x32_bf16 v[58:61], v[164:167], v[188:191], v[58:61]
	v_mfma_f32_16x16x32_bf16 v[46:49], v[156:159], v[196:199], v[46:49]
	v_mfma_f32_16x16x32_bf16 v[42:45], v[164:167], v[196:199], v[42:45]
	v_mfma_f32_16x16x32_bf16 v[30:33], v[156:159], v[204:207], v[30:33]
	v_mfma_f32_16x16x32_bf16 v[26:29], v[164:167], v[204:207], v[26:29]
	v_mfma_f32_16x16x32_bf16 v[14:17], v[156:159], v[212:215], v[14:17]
	v_mfma_f32_16x16x32_bf16 v[10:13], v[164:167], v[212:215], v[10:13]
	s_setprio 0
	s_setprio 1
	v_mfma_f32_16x16x32_bf16 v[54:57], v[168:171], v[184:187], v[54:57]
	v_mfma_f32_16x16x32_bf16 v[50:53], v[176:179], v[184:187], v[50:53]
	v_mfma_f32_16x16x32_bf16 v[38:41], v[168:171], v[192:195], v[38:41]
	v_mfma_f32_16x16x32_bf16 v[34:37], v[176:179], v[192:195], v[34:37]
	v_mfma_f32_16x16x32_bf16 v[22:25], v[168:171], v[200:203], v[22:25]
	v_mfma_f32_16x16x32_bf16 v[18:21], v[176:179], v[200:203], v[18:21]
	v_mfma_f32_16x16x32_bf16 v[6:9], v[168:171], v[208:211], v[6:9]
	v_mfma_f32_16x16x32_bf16 v[2:5], v[176:179], v[208:211], v[2:5]
	v_mfma_f32_16x16x32_bf16 v[54:57], v[172:175], v[188:191], v[54:57]
	v_mfma_f32_16x16x32_bf16 v[50:53], v[180:183], v[188:191], v[50:53]
	v_mfma_f32_16x16x32_bf16 v[38:41], v[172:175], v[196:199], v[38:41]
	v_mfma_f32_16x16x32_bf16 v[34:37], v[180:183], v[196:199], v[34:37]
	v_mfma_f32_16x16x32_bf16 v[22:25], v[172:175], v[204:207], v[22:25]
	v_mfma_f32_16x16x32_bf16 v[18:21], v[180:183], v[204:207], v[18:21]
	v_mfma_f32_16x16x32_bf16 v[6:9], v[172:175], v[212:215], v[6:9]
	v_mfma_f32_16x16x32_bf16 v[2:5], v[180:183], v[212:215], v[2:5]
	s_setprio 0
	s_barrier
	s_add_i32 s49, 0, 0x18000
	s_add_i32 s50, 0, 0x1c000
	v_add_u32_e32 v164, s49, v147
	v_add_u32_e32 v252, s49, v249
	v_add_u32_e32 v180, s50, v147
	v_add_u32_e32 v253, s50, v249
	ds_read_b128 v[152:155], v164
	ds_read_b128 v[156:159], v252
	ds_read_b128 v[160:163], v164 offset:2048
	ds_read_b128 v[164:167], v252 offset:2048
	ds_read_b128 v[168:171], v180
	ds_read_b128 v[172:175], v253
	ds_read_b128 v[176:179], v180 offset:2048
	ds_read_b128 v[180:183], v253 offset:2048
	s_add_u32 s24, s24, 0x80000
	s_addc_u32 s25, s25, 0
	s_add_u32 s100, s24, 0xfff80080
	s_addc_u32 s101, s25, -1
	s_mov_b32 m0, s34
	ds_read_b128 v[184:187], v151 offset:32768
	ds_read_b128 v[188:191], v248 offset:32768
	ds_read_b128 v[192:195], v151 offset:34816
	ds_read_b128 v[196:199], v248 offset:34816
	ds_read_b128 v[200:203], v151 offset:36864
	ds_read_b128 v[204:207], v248 offset:36864
	ds_read_b128 v[208:211], v151 offset:38912
	ds_read_b128 v[212:215], v248 offset:38912
	global_load_lds_dwordx4 v130, s[24:25]
	s_mov_b32 m0, s35
	s_nop 0
	global_load_lds_dwordx4 v134, s[24:25]
	s_waitcnt vmcnt(8)
	s_waitcnt lgkmcnt(0)
	s_barrier
	s_setprio 1
	s_waitcnt lgkmcnt(0)
	v_mfma_f32_16x16x32_bf16 v[126:129], v[152:155], v[184:187], v[126:129]
	v_mfma_f32_16x16x32_bf16 v[122:125], v[160:163], v[184:187], v[122:125]
	v_mfma_f32_16x16x32_bf16 v[110:113], v[152:155], v[192:195], v[110:113]
	v_mfma_f32_16x16x32_bf16 v[106:109], v[160:163], v[192:195], v[106:109]
	v_mfma_f32_16x16x32_bf16 v[94:97], v[152:155], v[200:203], v[94:97]
	v_mfma_f32_16x16x32_bf16 v[90:93], v[160:163], v[200:203], v[90:93]
	v_mfma_f32_16x16x32_bf16 v[78:81], v[152:155], v[208:211], v[78:81]
	v_mfma_f32_16x16x32_bf16 v[74:77], v[160:163], v[208:211], v[74:77]
	v_mfma_f32_16x16x32_bf16 v[126:129], v[156:159], v[188:191], v[126:129]
	v_mfma_f32_16x16x32_bf16 v[122:125], v[164:167], v[188:191], v[122:125]
	v_mfma_f32_16x16x32_bf16 v[110:113], v[156:159], v[196:199], v[110:113]
	v_mfma_f32_16x16x32_bf16 v[106:109], v[164:167], v[196:199], v[106:109]
	v_mfma_f32_16x16x32_bf16 v[94:97], v[156:159], v[204:207], v[94:97]
	v_mfma_f32_16x16x32_bf16 v[90:93], v[164:167], v[204:207], v[90:93]
	v_mfma_f32_16x16x32_bf16 v[78:81], v[156:159], v[212:215], v[78:81]
	v_mfma_f32_16x16x32_bf16 v[74:77], v[164:167], v[212:215], v[74:77]
	s_setprio 0
	s_setprio 1
	v_mfma_f32_16x16x32_bf16 v[118:121], v[168:171], v[184:187], v[118:121]
	v_mfma_f32_16x16x32_bf16 v[114:117], v[176:179], v[184:187], v[114:117]
	v_mfma_f32_16x16x32_bf16 v[102:105], v[168:171], v[192:195], v[102:105]
	v_mfma_f32_16x16x32_bf16 v[98:101], v[176:179], v[192:195], v[98:101]
	v_mfma_f32_16x16x32_bf16 v[86:89], v[168:171], v[200:203], v[86:89]
	v_mfma_f32_16x16x32_bf16 v[82:85], v[176:179], v[200:203], v[82:85]
	v_mfma_f32_16x16x32_bf16 v[70:73], v[168:171], v[208:211], v[70:73]
	v_mfma_f32_16x16x32_bf16 v[66:69], v[176:179], v[208:211], v[66:69]
	v_mfma_f32_16x16x32_bf16 v[118:121], v[172:175], v[188:191], v[118:121]
	v_mfma_f32_16x16x32_bf16 v[114:117], v[180:183], v[188:191], v[114:117]
	v_mfma_f32_16x16x32_bf16 v[102:105], v[172:175], v[196:199], v[102:105]
	v_mfma_f32_16x16x32_bf16 v[98:101], v[180:183], v[196:199], v[98:101]
	v_mfma_f32_16x16x32_bf16 v[86:89], v[172:175], v[204:207], v[86:89]
	v_mfma_f32_16x16x32_bf16 v[82:85], v[180:183], v[204:207], v[82:85]
	v_mfma_f32_16x16x32_bf16 v[70:73], v[172:175], v[212:215], v[70:73]
	v_mfma_f32_16x16x32_bf16 v[66:69], v[180:183], v[212:215], v[66:69]
	s_setprio 0
	s_barrier
	s_add_i32 s24, s49, s30
	s_mov_b32 m0, s24
	ds_read_b128 v[184:187], v151 offset:49152
	ds_read_b128 v[188:191], v248 offset:49152
	ds_read_b128 v[192:195], v151 offset:51200
	ds_read_b128 v[196:199], v248 offset:51200
	ds_read_b128 v[200:203], v151 offset:53248
	ds_read_b128 v[204:207], v248 offset:53248
	ds_read_b128 v[208:211], v151 offset:55296
	ds_read_b128 v[212:215], v248 offset:55296
	s_add_u32 s98, s22, 0x80
	s_addc_u32 s99, s23, 0
	global_load_lds_dwordx4 v132, s[98:99]
	s_add_i32 m0, s24, 0x2000
	s_add_u32 s22, s22, 0x80080
	s_addc_u32 s23, s23, 0
	s_add_i32 s24, s50, s30
	global_load_lds_dwordx4 v136, s[98:99]
	s_mov_b32 m0, s24
	s_nop 0
	global_load_lds_dwordx4 v132, s[22:23]
	s_add_i32 m0, s24, 0x2000
	s_nop 0
	global_load_lds_dwordx4 v136, s[22:23]
	s_mov_b32 m0, s38
	s_nop 0
	global_load_lds_dwordx4 v130, s[100:101]
	s_mov_b32 m0, s39
	s_nop 0
	global_load_lds_dwordx4 v134, s[100:101]
	s_waitcnt vmcnt(8)
	s_waitcnt lgkmcnt(0)
	s_barrier
	s_setprio 1
	s_waitcnt lgkmcnt(0)
	v_mfma_f32_16x16x32_bf16 v[62:65], v[152:155], v[184:187], v[62:65]
	v_mfma_f32_16x16x32_bf16 v[58:61], v[160:163], v[184:187], v[58:61]
	v_mfma_f32_16x16x32_bf16 v[46:49], v[152:155], v[192:195], v[46:49]
	v_mfma_f32_16x16x32_bf16 v[42:45], v[160:163], v[192:195], v[42:45]
	v_mfma_f32_16x16x32_bf16 v[30:33], v[152:155], v[200:203], v[30:33]
	v_mfma_f32_16x16x32_bf16 v[26:29], v[160:163], v[200:203], v[26:29]
	v_mfma_f32_16x16x32_bf16 v[14:17], v[152:155], v[208:211], v[14:17]
	v_mfma_f32_16x16x32_bf16 v[10:13], v[160:163], v[208:211], v[10:13]
	v_mfma_f32_16x16x32_bf16 v[62:65], v[156:159], v[188:191], v[62:65]
	v_mfma_f32_16x16x32_bf16 v[58:61], v[164:167], v[188:191], v[58:61]
	v_mfma_f32_16x16x32_bf16 v[46:49], v[156:159], v[196:199], v[46:49]
	v_mfma_f32_16x16x32_bf16 v[42:45], v[164:167], v[196:199], v[42:45]
	v_mfma_f32_16x16x32_bf16 v[30:33], v[156:159], v[204:207], v[30:33]
	v_mfma_f32_16x16x32_bf16 v[26:29], v[164:167], v[204:207], v[26:29]
	v_mfma_f32_16x16x32_bf16 v[14:17], v[156:159], v[212:215], v[14:17]
	v_mfma_f32_16x16x32_bf16 v[10:13], v[164:167], v[212:215], v[10:13]
	s_setprio 0
	s_setprio 1
	v_mfma_f32_16x16x32_bf16 v[54:57], v[168:171], v[184:187], v[54:57]
	v_mfma_f32_16x16x32_bf16 v[50:53], v[176:179], v[184:187], v[50:53]
	v_mfma_f32_16x16x32_bf16 v[38:41], v[168:171], v[192:195], v[38:41]
	v_mfma_f32_16x16x32_bf16 v[34:37], v[176:179], v[192:195], v[34:37]
	v_mfma_f32_16x16x32_bf16 v[22:25], v[168:171], v[200:203], v[22:25]
	v_mfma_f32_16x16x32_bf16 v[18:21], v[176:179], v[200:203], v[18:21]
	v_mfma_f32_16x16x32_bf16 v[6:9], v[168:171], v[208:211], v[6:9]
	v_mfma_f32_16x16x32_bf16 v[2:5], v[176:179], v[208:211], v[2:5]
	v_mfma_f32_16x16x32_bf16 v[54:57], v[172:175], v[188:191], v[54:57]
	v_mfma_f32_16x16x32_bf16 v[50:53], v[180:183], v[188:191], v[50:53]
	v_mfma_f32_16x16x32_bf16 v[38:41], v[172:175], v[196:199], v[38:41]
	v_mfma_f32_16x16x32_bf16 v[34:37], v[180:183], v[196:199], v[34:37]
	v_mfma_f32_16x16x32_bf16 v[22:25], v[172:175], v[204:207], v[22:25]
	v_mfma_f32_16x16x32_bf16 v[18:21], v[180:183], v[204:207], v[18:21]
	v_mfma_f32_16x16x32_bf16 v[6:9], v[172:175], v[212:215], v[6:9]
	v_mfma_f32_16x16x32_bf16 v[2:5], v[180:183], v[212:215], v[2:5]
	s_setprio 0
	s_barrier
	s_add_i32 s48, s48, 2
	s_add_u32 s20, s20, 0x100
	s_addc_u32 s21, s21, 0
	s_add_u32 s46, s46, 0x100
	s_addc_u32 s47, s47, 0
	s_cmp_gt_u32 s48, 29
	s_cbranch_scc0 .LBB0_1135
	v_readlane_b32 s44, v254, 52
	s_and_b64 vcc, exec, s[8:9]
	v_readlane_b32 s45, v254, 53
	v_readlane_b32 s46, v254, 54
	v_readlane_b32 s47, v254, 55
	s_cbranch_vccz .LBB0_1138
	s_barrier

.LBB0_1204:
	s_cmp_lt_i32 s44, 8
	s_cselect_b64 s[0:1], -1, 0
	s_cmp_gt_i32 s45, 7
	s_cselect_b64 s[2:3], -1, 0
	s_and_b64 s[0:1], s[0:1], s[2:3]
	v_readlane_b32 s48, v254, 11
	s_andn2_b64 vcc, exec, s[0:1]
	v_readlane_b32 s54, v254, 17
	v_readlane_b32 s55, v254, 18
	v_readlane_b32 s49, v254, 12
	v_readlane_b32 s50, v254, 13
	v_readlane_b32 s51, v254, 14
	v_readlane_b32 s52, v254, 15
	v_readlane_b32 s53, v254, 16
	v_readlane_b32 s56, v254, 19
	v_readlane_b32 s57, v254, 20
	v_readlane_b32 s58, v254, 21
	v_readlane_b32 s59, v254, 22
	v_readlane_b32 s60, v254, 23
	v_readlane_b32 s61, v254, 24
	v_readlane_b32 s62, v254, 25
	v_readlane_b32 s63, v254, 26
	s_cbranch_vccnz .LBB0_1289
	s_cmpk_gt_i32 s43, 0xff
	v_readfirstlane_b32 s0, v0
	s_cbranch_scc1 .LBB0_1235
	v_lshlrev_b32_e32 v1, 4, v0
	v_and_b32_e32 v2, 32, v0
	v_bitop3_b32 v10, v1, v2, 48 bitop3:0x6c
	v_lshrrev_b32_e32 v2, 1, v0
	v_and_b32_e32 v12, 24, v2
	v_lshrrev_b32_e32 v2, 5, v0
	s_add_u32 s30, s68, 0x2c400000
	v_and_b32_e32 v2, 4, v2
	v_bfe_u32 v4, v0, 2, 2
	s_addc_u32 s31, s69, 0
	v_bfe_u32 v3, v0, 2, 4
	v_and_b32_e32 v11, 64, v0
	v_or3_b32 v2, v2, v4, v12
	v_lshrrev_b32_e32 v4, 3, v0
	s_add_u32 s4, s68, 0x7400000
	v_or_b32_e32 v1, v10, v11
	v_and_or_b32 v5, v4, 48, v3
	v_and_or_b32 v4, v4, 32, v2
	s_addc_u32 s5, s69, 0
	v_lshrrev_b32_e32 v1, 1, v1
	v_mul_u32_u24_e32 v4, 0x1600, v4
	s_ashr_i32 s34, s43, 31
	v_or_b32_e32 v4, v4, v1
	s_lshr_b32 s2, s34, 29
	v_lshlrev_b32_e32 v132, 1, v4
	v_bfe_u32 v4, v0, 3, 25
	s_add_i32 s2, s43, s2
	v_or_b32_e32 v4, 64, v4
	s_movk_i32 s1, 0x70
	s_ashr_i32 s6, s2, 3
	s_and_b32 s2, s2, -8
	v_and_or_b32 v3, v4, s1, v3
	s_movk_i32 s1, 0x60
	s_lshr_b32 s3, s0, 6
	s_sub_i32 s2, s43, s2
	v_and_or_b32 v2, v4, s1, v2
	s_lshr_b32 s1, s0, 8
	s_lshl_b32 s33, s3, 10
	s_lshl_b32 s8, s2, 5
	s_mul_i32 s7, s2, 33
	s_cmp_lt_i32 s2, 0
	s_cselect_b32 s2, s7, s8
	s_add_i32 s2, s2, s6
	s_ashr_i32 s6, s2, 31
	s_lshr_b32 s6, s6, 27
	s_add_i32 s6, s2, s6
	s_ashr_i32 s7, s6, 5
	s_and_b32 s6, s6, 0xffe0
	s_sub_i32 s6, s2, s6
	s_bfe_i32 s2, s6, 0x80000
	s_bfe_u32 s2, s2, 0x2000d
	s_add_i32 s8, s6, s2
	s_bfe_i32 s2, s8, 0x80000
	s_and_b32 s8, s8, 0xfc
	s_sub_i32 s6, s6, s8
	s_lshl_b32 s7, s7, 2
	s_sext_i32_i16 s9, s2
	s_sext_i32_i8 s6, s6
	s_add_i32 s51, s7, s6
	s_ashr_i32 s6, s9, 2
	s_lshr_b32 s2, s9, 2
	s_mul_hi_i32 s7, s6, 0x2c0000
	s_mul_i32 s6, s6, 0x2c0000
	s_add_u32 s26, s4, s6
	s_addc_u32 s27, s5, s7
	s_add_i32 s35, s33, 0
	v_mul_u32_u24_e32 v13, 0x1600, v5
	v_mul_u32_u24_e32 v14, 0x1600, v3
	v_mul_u32_u24_e32 v2, 0x1600, v2
	s_add_i32 m0, s35, 0x10000
	v_or_b32_e32 v5, v1, v13
	v_or_b32_e32 v3, v14, v1
	v_or_b32_e32 v1, v2, v1
	v_lshrrev_b32_e32 v240, 6, v0
	v_bfe_u32 v241, v0, 3, 3
	v_and_b32_e32 v242, 7, v0
	v_lshrrev_b32_e32 v243, 1, v241
	v_and_b32_e32 v244, 1, v240
	v_lshl_or_b32 v243, v244, 2, v243
	v_xor_b32_e32 v242, v242, v243
	v_lshlrev_b32_e32 v242, 4, v242
	v_lshl_add_u32 v245, v240, 3, v241
	v_lshrrev_b32_e32 v246, 2, v240
	v_lshlrev_b32_e32 v246, 5, v246
	v_lshl_add_u32 v246, v244, 4, v246
	v_lshrrev_b32_e32 v247, 2, v241
	v_lshl_add_u32 v246, v247, 3, v246
	v_bfe_u32 v247, v240, 1, 1
	v_lshl_add_u32 v246, v247, 2, v246
	v_and_b32_e32 v247, 3, v241
	v_add_u32_e32 v246, v246, v247
	v_mov_b32_e32 v247, 0x2c00
	v_mad_u32_u24 v130, v245, v247, v242
	v_mad_u32_u24 v132, v246, v247, v242
	v_add_u32_e32 v134, 0xb0000, v130
	v_add_u32_e32 v136, 0xb0000, v132
	global_load_lds_dwordx4 v132, s[26:27]
	s_add_i32 m0, s35, 0x12000
	s_nop 0
	s_add_u32 s6, s26, 0x160000
	global_load_lds_dwordx4 v136, s[26:27]
	s_addc_u32 s7, s27, 0
	s_add_i32 m0, s35, 0x14000
	s_mul_i32 s10, s51, 0x2c0000
	global_load_lds_dwordx4 v132, s[6:7]
	s_add_i32 m0, s35, 0x16000
	s_mul_hi_i32 s8, s51, 0x2c0000
	s_add_u32 s24, s30, s10
	s_addc_u32 s25, s31, s8
	s_add_i32 s36, s35, 0x2000
	s_nop 0
	global_load_lds_dwordx4 v136, s[6:7]
	s_mov_b32 m0, s35
	s_add_u32 s6, s24, 0x160000
	s_nop 0
	global_load_lds_dwordx4 v130, s[24:25]
	s_mov_b32 m0, s36
	s_addc_u32 s7, s25, 0
	s_add_i32 s37, s35, 0x4000
	global_load_lds_dwordx4 v134, s[24:25]
	s_mov_b32 m0, s37
	s_add_i32 s38, s35, 0x6000
	global_load_lds_dwordx4 v130, s[6:7]
	s_mov_b32 m0, s38
	v_mov_b32_e32 v133, 0
	global_load_lds_dwordx4 v134, s[6:7]
	v_mov_b32_e32 v137, v133
	v_mov_b32_e32 v131, v133
	v_mov_b32_e32 v135, v133
	s_cmp_eq_u32 s1, 1
	s_mov_b32 s39, 0
	v_lshl_add_u64 v[8:9], s[26:27], 0, v[132:133]
	v_lshl_add_u64 v[6:7], s[26:27], 0, v[136:137]
	v_lshl_add_u64 v[2:3], s[24:25], 0, v[130:131]
	s_cselect_b64 s[6:7], -1, 0
	s_cmp_lg_u32 s1, 1
	v_lshl_add_u64 v[4:5], s[24:25], 0, v[134:135]
	s_cbranch_scc1 .LBB0_1208
	s_barrier
.LBB0_1208:
	s_add_u32 s8, s68, 0x32000000
	v_readlane_b32 s10, v254, 2
	s_addc_u32 s9, s69, 0
	s_ashr_i32 s40, s10, 31
	s_lshl_b32 s3, s3, 5
	s_mov_b64 s[10:11], 0x80
	s_and_b32 s3, s3, 0x60
	s_add_i32 m0, s35, 0x18000
	v_lshl_add_u64 v[8:9], v[8:9], 0, s[10:11]
	s_lshl_b32 s14, s1, 13
	s_lshl_b32 s15, s3, 7
	s_waitcnt vmcnt(2)
	s_barrier
	global_load_lds_dwordx4 v[8:9], off
	v_lshl_add_u64 v[6:7], v[6:7], 0, s[10:11]
	s_add_i32 m0, s35, 0x1a000
	s_add_i32 s41, s35, 0x8000
	s_add_i32 s42, s35, 0xa000
	global_load_lds_dwordx4 v[6:7], off
	v_lshl_add_u64 v[2:3], v[2:3], 0, s[10:11]
	s_mov_b32 m0, s41
	s_add_u32 s12, s26, 0x160080
	global_load_lds_dwordx4 v[2:3], off
	v_lshl_add_u64 v[2:3], v[4:5], 0, s[10:11]
	s_mov_b32 m0, s42
	s_addc_u32 s13, s27, 0
	global_load_lds_dwordx4 v[2:3], off
	s_add_i32 m0, s35, 0x1c000
	v_lshl_add_u64 v[2:3], s[12:13], 0, v[132:133]
	global_load_lds_dwordx4 v[2:3], off
	v_lshl_add_u64 v[2:3], s[12:13], 0, v[136:137]
	s_add_i32 m0, s35, 0x1e000
	s_sext_i32_i8 s52, s2
	global_load_lds_dwordx4 v[2:3], off
	v_lshlrev_b32_e32 v3, 1, v12
	v_lshlrev_b32_e32 v1, 6, v0
	s_movk_i32 s2, 0x3c0
	v_and_b32_e32 v2, 15, v0
	v_and_or_b32 v4, v1, s2, v3
	v_lshlrev_b32_e32 v1, 2, v0
	v_and_b32_e32 v5, 32, v1
	v_lshl_or_b32 v1, s1, 6, v2
	v_lshl_or_b32 v2, v2, 6, v3
	s_waitcnt vmcnt(6)
	s_cmpk_lt_u32 s0, 0x100
	v_add_u16_e32 v3, v10, v11
	v_bitop3_b32 v2, v2, s14, v5 bitop3:0xde
	v_bitop3_b32 v146, s15, v4, v5 bitop3:0xf6
	s_cselect_b64 s[12:13], -1, 0
	v_lshrrev_b16_e32 v3, 1, v3
	s_add_i32 s43, 0, 0x10000
	s_add_i32 s44, 0, 0x14000
	v_or_b32_e32 v147, s3, v12
	v_add_lshl_u32 v138, v13, v3, 1
	v_mov_b32_e32 v139, v133
	v_add_lshl_u32 v140, v14, v3, 1
	v_mov_b32_e32 v141, v133
	v_mov_b64_e32 v[142:143], 0x100
	v_mov_b64_e32 v[144:145], 0xff
	v_add_u32_e32 v148, s43, v146
	v_add_u32_e32 v149, s44, v146
	v_add_u32_e32 v150, 0, v2
	s_mov_b64 s[14:15], 0x80000
	s_mov_b32 s45, 0x80000
	s_mov_b64 s[16:17], 0x90000
	s_mov_b32 s46, 0x90000
	s_mov_b64 s[18:19], 0xa0000
	s_mov_b32 s47, 0xa0000
	s_mov_b64 s[20:21], 0xb0000
	s_mov_b32 s48, 0xb0000
	s_barrier
	v_mov_b32_e32 v138, v130
	v_mov_b32_e32 v140, v134
	v_and_b32_e32 v240, 63, v0
	v_and_b32_e32 v241, 15, v240
	v_lshrrev_b32_e32 v242, 4, v240
	v_lshrrev_b32_e32 v243, 3, v241
	v_lshlrev_b32_e32 v243, 10, v243
	v_and_b32_e32 v244, 7, v241
	v_lshl_add_u32 v243, v244, 7, v243
	v_lshrrev_b32_e32 v244, 1, v241
	v_xor_b32_e32 v245, v242, v244
	v_lshl_add_u32 v245, v245, 4, v243
	v_xor_b32_e32 v246, 64, v245
	v_lshrrev_b32_e32 v247, 6, v0
	v_lshrrev_b32_e32 v244, 2, v247
	v_lshl_add_u32 v150, v244, 13, v245
	v_lshl_add_u32 v248, v244, 13, v246
	v_and_b32_e32 v244, 3, v247
	v_lshl_add_u32 v146, v244, 12, v245
	v_lshl_add_u32 v249, v244, 12, v246
	v_add_u32_e32 v148, s43, v146
	v_add_u32_e32 v250, s43, v249
	v_add_u32_e32 v149, s44, v146
	v_add_u32_e32 v251, s44, v249
	s_branch .LBB0_1211

.LBB0_1222:
	ds_read_b128 v[152:155], v148
	ds_read_b128 v[156:159], v250
	ds_read_b128 v[160:163], v148 offset:2048
	ds_read_b128 v[164:167], v250 offset:2048
	ds_read_b128 v[168:171], v149
	ds_read_b128 v[172:175], v251
	ds_read_b128 v[176:179], v149 offset:2048
	ds_read_b128 v[180:183], v251 offset:2048
	s_add_u32 s26, s24, 0xffea0080
	s_addc_u32 s27, s25, -1
	s_cmpk_eq_i32 s55, 0x54
	s_cselect_b32 s29, s3, s27
	s_cselect_b32 s28, s2, s26
	s_cselect_b32 s27, s23, s54
	s_cselect_b32 s26, s22, s53
	s_add_i32 m0, s35, 0xc000
	ds_read_b128 v[184:187], v150
	ds_read_b128 v[188:191], v248
	ds_read_b128 v[192:195], v150 offset:2048
	ds_read_b128 v[196:199], v248 offset:2048
	ds_read_b128 v[200:203], v150 offset:4096
	ds_read_b128 v[204:207], v248 offset:4096
	ds_read_b128 v[208:211], v150 offset:6144
	ds_read_b128 v[212:215], v248 offset:6144
	global_load_lds_dwordx4 v138, s[24:25]
	s_add_i32 m0, s35, 0xe000
	s_nop 0
	global_load_lds_dwordx4 v140, s[24:25]
	s_waitcnt vmcnt(8)
	s_waitcnt lgkmcnt(0)
	s_barrier
	s_setprio 1
	s_waitcnt lgkmcnt(0)
	v_mfma_f32_16x16x32_bf16 v[126:129], v[152:155], v[184:187], v[126:129]
	v_mfma_f32_16x16x32_bf16 v[122:125], v[160:163], v[184:187], v[122:125]
	v_mfma_f32_16x16x32_bf16 v[118:121], v[152:155], v[192:195], v[118:121]
	v_mfma_f32_16x16x32_bf16 v[110:113], v[160:163], v[192:195], v[110:113]
	v_mfma_f32_16x16x32_bf16 v[102:105], v[152:155], v[200:203], v[102:105]
	v_mfma_f32_16x16x32_bf16 v[94:97], v[160:163], v[200:203], v[94:97]
	v_mfma_f32_16x16x32_bf16 v[86:89], v[152:155], v[208:211], v[86:89]
	v_mfma_f32_16x16x32_bf16 v[78:81], v[160:163], v[208:211], v[78:81]
	v_mfma_f32_16x16x32_bf16 v[126:129], v[156:159], v[188:191], v[126:129]
	v_mfma_f32_16x16x32_bf16 v[122:125], v[164:167], v[188:191], v[122:125]
	v_mfma_f32_16x16x32_bf16 v[118:121], v[156:159], v[196:199], v[118:121]
	v_mfma_f32_16x16x32_bf16 v[110:113], v[164:167], v[196:199], v[110:113]
	v_mfma_f32_16x16x32_bf16 v[102:105], v[156:159], v[204:207], v[102:105]
	v_mfma_f32_16x16x32_bf16 v[94:97], v[164:167], v[204:207], v[94:97]
	v_mfma_f32_16x16x32_bf16 v[86:89], v[156:159], v[212:215], v[86:89]
	v_mfma_f32_16x16x32_bf16 v[78:81], v[164:167], v[212:215], v[78:81]
	s_setprio 0
	s_setprio 1
	v_mfma_f32_16x16x32_bf16 v[114:117], v[168:171], v[184:187], v[114:117]
	v_mfma_f32_16x16x32_bf16 v[106:109], v[176:179], v[184:187], v[106:109]
	v_mfma_f32_16x16x32_bf16 v[98:101], v[168:171], v[192:195], v[98:101]
	v_mfma_f32_16x16x32_bf16 v[90:93], v[176:179], v[192:195], v[90:93]
	v_mfma_f32_16x16x32_bf16 v[82:85], v[168:171], v[200:203], v[82:85]
	v_mfma_f32_16x16x32_bf16 v[74:77], v[176:179], v[200:203], v[74:77]
	v_mfma_f32_16x16x32_bf16 v[70:73], v[168:171], v[208:211], v[70:73]
	v_mfma_f32_16x16x32_bf16 v[66:69], v[176:179], v[208:211], v[66:69]
	v_mfma_f32_16x16x32_bf16 v[114:117], v[172:175], v[188:191], v[114:117]
	v_mfma_f32_16x16x32_bf16 v[106:109], v[180:183], v[188:191], v[106:109]
	v_mfma_f32_16x16x32_bf16 v[98:101], v[172:175], v[196:199], v[98:101]
	v_mfma_f32_16x16x32_bf16 v[90:93], v[180:183], v[196:199], v[90:93]
	v_mfma_f32_16x16x32_bf16 v[82:85], v[172:175], v[204:207], v[82:85]
	v_mfma_f32_16x16x32_bf16 v[74:77], v[180:183], v[204:207], v[74:77]
	v_mfma_f32_16x16x32_bf16 v[70:73], v[172:175], v[212:215], v[70:73]
	v_mfma_f32_16x16x32_bf16 v[66:69], v[180:183], v[212:215], v[66:69]
	s_setprio 0
	s_barrier
	s_add_i32 s56, s43, s33
	s_mov_b32 m0, s56
	ds_read_b128 v[184:187], v150 offset:16384
	ds_read_b128 v[188:191], v248 offset:16384
	ds_read_b128 v[192:195], v150 offset:18432
	ds_read_b128 v[196:199], v248 offset:18432
	ds_read_b128 v[200:203], v150 offset:20480
	ds_read_b128 v[204:207], v248 offset:20480
	ds_read_b128 v[208:211], v150 offset:22528
	ds_read_b128 v[212:215], v248 offset:22528
	global_load_lds_dwordx4 v132, s[26:27]
	s_add_i32 m0, s56, 0x2000
	s_add_u32 s56, s26, 0x160000
	s_addc_u32 s57, s27, 0
	s_add_i32 s58, s44, s33
	global_load_lds_dwordx4 v136, s[26:27]
	s_mov_b32 m0, s58
	s_nop 0
	global_load_lds_dwordx4 v132, s[56:57]
	s_add_i32 m0, s58, 0x2000
	s_nop 0
	global_load_lds_dwordx4 v136, s[56:57]
	s_mov_b32 m0, s35
	s_nop 0
	global_load_lds_dwordx4 v130, s[28:29]
	s_mov_b32 m0, s36
	s_nop 0
	global_load_lds_dwordx4 v134, s[28:29]
	s_waitcnt vmcnt(8)
	s_waitcnt lgkmcnt(0)
	s_barrier
	s_setprio 1
	s_waitcnt lgkmcnt(0)
	v_mfma_f32_16x16x32_bf16 v[62:65], v[152:155], v[184:187], v[62:65]
	v_mfma_f32_16x16x32_bf16 v[58:61], v[160:163], v[184:187], v[58:61]
	v_mfma_f32_16x16x32_bf16 v[54:57], v[152:155], v[192:195], v[54:57]
	v_mfma_f32_16x16x32_bf16 v[46:49], v[160:163], v[192:195], v[46:49]
	v_mfma_f32_16x16x32_bf16 v[38:41], v[152:155], v[200:203], v[38:41]
	v_mfma_f32_16x16x32_bf16 v[30:33], v[160:163], v[200:203], v[30:33]
	v_mfma_f32_16x16x32_bf16 v[22:25], v[152:155], v[208:211], v[22:25]
	v_mfma_f32_16x16x32_bf16 v[14:17], v[160:163], v[208:211], v[14:17]
	v_mfma_f32_16x16x32_bf16 v[62:65], v[156:159], v[188:191], v[62:65]
	v_mfma_f32_16x16x32_bf16 v[58:61], v[164:167], v[188:191], v[58:61]
	v_mfma_f32_16x16x32_bf16 v[54:57], v[156:159], v[196:199], v[54:57]
	v_mfma_f32_16x16x32_bf16 v[46:49], v[164:167], v[196:199], v[46:49]
	v_mfma_f32_16x16x32_bf16 v[38:41], v[156:159], v[204:207], v[38:41]
	v_mfma_f32_16x16x32_bf16 v[30:33], v[164:167], v[204:207], v[30:33]
	v_mfma_f32_16x16x32_bf16 v[22:25], v[156:159], v[212:215], v[22:25]
	v_mfma_f32_16x16x32_bf16 v[14:17], v[164:167], v[212:215], v[14:17]
	s_setprio 0
	s_setprio 1
	v_mfma_f32_16x16x32_bf16 v[50:53], v[168:171], v[184:187], v[50:53]
	v_mfma_f32_16x16x32_bf16 v[42:45], v[176:179], v[184:187], v[42:45]
	v_mfma_f32_16x16x32_bf16 v[34:37], v[168:171], v[192:195], v[34:37]
	v_mfma_f32_16x16x32_bf16 v[26:29], v[176:179], v[192:195], v[26:29]
	v_mfma_f32_16x16x32_bf16 v[18:21], v[168:171], v[200:203], v[18:21]
	v_mfma_f32_16x16x32_bf16 v[10:13], v[176:179], v[200:203], v[10:13]
	v_mfma_f32_16x16x32_bf16 v[6:9], v[168:171], v[208:211], v[6:9]
	v_mfma_f32_16x16x32_bf16 v[2:5], v[176:179], v[208:211], v[2:5]
	v_mfma_f32_16x16x32_bf16 v[50:53], v[172:175], v[188:191], v[50:53]
	v_mfma_f32_16x16x32_bf16 v[42:45], v[180:183], v[188:191], v[42:45]
	v_mfma_f32_16x16x32_bf16 v[34:37], v[172:175], v[196:199], v[34:37]
	v_mfma_f32_16x16x32_bf16 v[26:29], v[180:183], v[196:199], v[26:29]
	v_mfma_f32_16x16x32_bf16 v[18:21], v[172:175], v[204:207], v[18:21]
	v_mfma_f32_16x16x32_bf16 v[10:13], v[180:183], v[204:207], v[10:13]
	v_mfma_f32_16x16x32_bf16 v[6:9], v[172:175], v[212:215], v[6:9]
	v_mfma_f32_16x16x32_bf16 v[2:5], v[180:183], v[212:215], v[2:5]
	s_setprio 0
	s_barrier
	s_add_i32 s56, 0, 0x18000
	v_add_u32_e32 v151, s56, v146
	v_add_u32_e32 v252, s56, v249
	s_add_i32 s57, 0, 0x1c000
	ds_read_b128 v[152:155], v151
	ds_read_b128 v[156:159], v252
	ds_read_b128 v[160:163], v151 offset:2048
	ds_read_b128 v[164:167], v252 offset:2048
	v_add_u32_e32 v151, s57, v146
	v_add_u32_e32 v253, s57, v249
	ds_read_b128 v[168:171], v151
	ds_read_b128 v[172:175], v253
	ds_read_b128 v[176:179], v151 offset:2048
	ds_read_b128 v[180:183], v253 offset:2048
	s_add_u32 s28, s28, 0x160000
	s_addc_u32 s29, s29, 0
	s_add_u32 s100, s28, 0xffea0080
	s_addc_u32 s101, s29, -1
	s_mov_b32 m0, s37
	ds_read_b128 v[184:187], v150 offset:32768
	ds_read_b128 v[188:191], v248 offset:32768
	ds_read_b128 v[192:195], v150 offset:34816
	ds_read_b128 v[196:199], v248 offset:34816
	ds_read_b128 v[200:203], v150 offset:36864
	ds_read_b128 v[204:207], v248 offset:36864
	ds_read_b128 v[208:211], v150 offset:38912
	ds_read_b128 v[212:215], v248 offset:38912
	global_load_lds_dwordx4 v130, s[28:29]
	s_mov_b32 m0, s38
	s_nop 0
	global_load_lds_dwordx4 v134, s[28:29]
	s_waitcnt vmcnt(8)
	s_waitcnt lgkmcnt(0)
	s_barrier
	s_setprio 1
	s_waitcnt lgkmcnt(0)
	v_mfma_f32_16x16x32_bf16 v[126:129], v[152:155], v[184:187], v[126:129]
	v_mfma_f32_16x16x32_bf16 v[122:125], v[160:163], v[184:187], v[122:125]
	v_mfma_f32_16x16x32_bf16 v[118:121], v[152:155], v[192:195], v[118:121]
	v_mfma_f32_16x16x32_bf16 v[110:113], v[160:163], v[192:195], v[110:113]
	v_mfma_f32_16x16x32_bf16 v[102:105], v[152:155], v[200:203], v[102:105]
	v_mfma_f32_16x16x32_bf16 v[94:97], v[160:163], v[200:203], v[94:97]
	v_mfma_f32_16x16x32_bf16 v[86:89], v[152:155], v[208:211], v[86:89]
	v_mfma_f32_16x16x32_bf16 v[78:81], v[160:163], v[208:211], v[78:81]
	v_mfma_f32_16x16x32_bf16 v[126:129], v[156:159], v[188:191], v[126:129]
	v_mfma_f32_16x16x32_bf16 v[122:125], v[164:167], v[188:191], v[122:125]
	v_mfma_f32_16x16x32_bf16 v[118:121], v[156:159], v[196:199], v[118:121]
	v_mfma_f32_16x16x32_bf16 v[110:113], v[164:167], v[196:199], v[110:113]
	v_mfma_f32_16x16x32_bf16 v[102:105], v[156:159], v[204:207], v[102:105]
	v_mfma_f32_16x16x32_bf16 v[94:97], v[164:167], v[204:207], v[94:97]
	v_mfma_f32_16x16x32_bf16 v[86:89], v[156:159], v[212:215], v[86:89]
	v_mfma_f32_16x16x32_bf16 v[78:81], v[164:167], v[212:215], v[78:81]
	s_setprio 0
	s_setprio 1
	v_mfma_f32_16x16x32_bf16 v[114:117], v[168:171], v[184:187], v[114:117]
	v_mfma_f32_16x16x32_bf16 v[106:109], v[176:179], v[184:187], v[106:109]
	v_mfma_f32_16x16x32_bf16 v[98:101], v[168:171], v[192:195], v[98:101]
	v_mfma_f32_16x16x32_bf16 v[90:93], v[176:179], v[192:195], v[90:93]
	v_mfma_f32_16x16x32_bf16 v[82:85], v[168:171], v[200:203], v[82:85]
	v_mfma_f32_16x16x32_bf16 v[74:77], v[176:179], v[200:203], v[74:77]
	v_mfma_f32_16x16x32_bf16 v[70:73], v[168:171], v[208:211], v[70:73]
	v_mfma_f32_16x16x32_bf16 v[66:69], v[176:179], v[208:211], v[66:69]
	v_mfma_f32_16x16x32_bf16 v[114:117], v[172:175], v[188:191], v[114:117]
	v_mfma_f32_16x16x32_bf16 v[106:109], v[180:183], v[188:191], v[106:109]
	v_mfma_f32_16x16x32_bf16 v[98:101], v[172:175], v[196:199], v[98:101]
	v_mfma_f32_16x16x32_bf16 v[90:93], v[180:183], v[196:199], v[90:93]
	v_mfma_f32_16x16x32_bf16 v[82:85], v[172:175], v[204:207], v[82:85]
	v_mfma_f32_16x16x32_bf16 v[74:77], v[180:183], v[204:207], v[74:77]
	v_mfma_f32_16x16x32_bf16 v[70:73], v[172:175], v[212:215], v[70:73]
	v_mfma_f32_16x16x32_bf16 v[66:69], v[180:183], v[212:215], v[66:69]
	s_setprio 0
	s_barrier
	s_add_i32 s28, s56, s33
	s_mov_b32 m0, s28
	ds_read_b128 v[184:187], v150 offset:49152
	ds_read_b128 v[188:191], v248 offset:49152
	ds_read_b128 v[192:195], v150 offset:51200
	ds_read_b128 v[196:199], v248 offset:51200
	ds_read_b128 v[200:203], v150 offset:53248
	ds_read_b128 v[204:207], v248 offset:53248
	ds_read_b128 v[208:211], v150 offset:55296
	ds_read_b128 v[212:215], v248 offset:55296
	s_add_u32 s98, s26, 0x80
	s_addc_u32 s99, s27, 0
	global_load_lds_dwordx4 v132, s[98:99]
	s_add_i32 m0, s28, 0x2000
	s_add_u32 s26, s26, 0x160080
	s_addc_u32 s27, s27, 0
	s_add_i32 s28, s57, s33
	global_load_lds_dwordx4 v136, s[98:99]
	s_mov_b32 m0, s28
	s_nop 0
	global_load_lds_dwordx4 v132, s[26:27]
	s_add_i32 m0, s28, 0x2000
	s_nop 0
	global_load_lds_dwordx4 v136, s[26:27]
	s_mov_b32 m0, s41
	s_nop 0
	global_load_lds_dwordx4 v130, s[100:101]
	s_mov_b32 m0, s42
	s_nop 0
	global_load_lds_dwordx4 v134, s[100:101]
	s_waitcnt vmcnt(8)
	s_waitcnt lgkmcnt(0)
	s_barrier
	s_setprio 1
	s_waitcnt lgkmcnt(0)
	v_mfma_f32_16x16x32_bf16 v[62:65], v[152:155], v[184:187], v[62:65]
	v_mfma_f32_16x16x32_bf16 v[58:61], v[160:163], v[184:187], v[58:61]
	v_mfma_f32_16x16x32_bf16 v[54:57], v[152:155], v[192:195], v[54:57]
	v_mfma_f32_16x16x32_bf16 v[46:49], v[160:163], v[192:195], v[46:49]
	v_mfma_f32_16x16x32_bf16 v[38:41], v[152:155], v[200:203], v[38:41]
	v_mfma_f32_16x16x32_bf16 v[30:33], v[160:163], v[200:203], v[30:33]
	v_mfma_f32_16x16x32_bf16 v[22:25], v[152:155], v[208:211], v[22:25]
	v_mfma_f32_16x16x32_bf16 v[14:17], v[160:163], v[208:211], v[14:17]
	v_mfma_f32_16x16x32_bf16 v[62:65], v[156:159], v[188:191], v[62:65]
	v_mfma_f32_16x16x32_bf16 v[58:61], v[164:167], v[188:191], v[58:61]
	v_mfma_f32_16x16x32_bf16 v[54:57], v[156:159], v[196:199], v[54:57]
	v_mfma_f32_16x16x32_bf16 v[46:49], v[164:167], v[196:199], v[46:49]
	v_mfma_f32_16x16x32_bf16 v[38:41], v[156:159], v[204:207], v[38:41]
	v_mfma_f32_16x16x32_bf16 v[30:33], v[164:167], v[204:207], v[30:33]
	v_mfma_f32_16x16x32_bf16 v[22:25], v[156:159], v[212:215], v[22:25]
	v_mfma_f32_16x16x32_bf16 v[14:17], v[164:167], v[212:215], v[14:17]
	s_setprio 0
	s_setprio 1
	v_mfma_f32_16x16x32_bf16 v[50:53], v[168:171], v[184:187], v[50:53]
	v_mfma_f32_16x16x32_bf16 v[42:45], v[176:179], v[184:187], v[42:45]
	v_mfma_f32_16x16x32_bf16 v[34:37], v[168:171], v[192:195], v[34:37]
	v_mfma_f32_16x16x32_bf16 v[26:29], v[176:179], v[192:195], v[26:29]
	v_mfma_f32_16x16x32_bf16 v[18:21], v[168:171], v[200:203], v[18:21]
	v_mfma_f32_16x16x32_bf16 v[10:13], v[176:179], v[200:203], v[10:13]
	v_mfma_f32_16x16x32_bf16 v[6:9], v[168:171], v[208:211], v[6:9]
	v_mfma_f32_16x16x32_bf16 v[2:5], v[176:179], v[208:211], v[2:5]
	v_mfma_f32_16x16x32_bf16 v[50:53], v[172:175], v[188:191], v[50:53]
	v_mfma_f32_16x16x32_bf16 v[42:45], v[180:183], v[188:191], v[42:45]
	v_mfma_f32_16x16x32_bf16 v[34:37], v[172:175], v[196:199], v[34:37]
	v_mfma_f32_16x16x32_bf16 v[26:29], v[180:183], v[196:199], v[26:29]
	v_mfma_f32_16x16x32_bf16 v[18:21], v[172:175], v[204:207], v[18:21]
	v_mfma_f32_16x16x32_bf16 v[10:13], v[180:183], v[204:207], v[10:13]
	v_mfma_f32_16x16x32_bf16 v[6:9], v[172:175], v[212:215], v[6:9]
	v_mfma_f32_16x16x32_bf16 v[2:5], v[180:183], v[212:215], v[2:5]
	s_setprio 0
	s_barrier
	s_add_i32 s55, s55, 2
	s_add_u32 s24, s24, 0x100
	s_addc_u32 s25, s25, 0
	s_add_u32 s53, s53, 0x100
	s_addc_u32 s54, s54, 0
	s_cmpk_gt_u32 s55, 0x55
	s_cbranch_scc0 .LBB0_1222
	s_and_b64 vcc, exec, s[12:13]
	s_cbranch_vccz .LBB0_1225
	s_barrier
